# v79 + K-loops: M0 written directly as wave offset + constant, 6-7 scratch SALU per 2 K-tiles removed
# baseline (speedup 1.0000x reference)
; #define PG8_STAGE(bufoff, gbase, voff) do { _Pragma("unroll") for (int _i = 0; _i < 2; ++_i) \
;         __builtin_amdgcn_global_load_lds((const unsigned*)((const char*)(gbase) + (voff)[_i]), (PG8_LAS unsigned*)(lds + (bufoff) + ldsw + _i * 8192), 16, 0, 0); } while (0)
; #define PG8_LDA(dst, b, h) do { _Pragma("unroll") for (int m = 0; m < 4; ++m) _Pragma("unroll") for (int k = 0; k < 2; ++k) dst[m][k] = *(const PG8_LAS bf16x8*)(lds + PG8_SA(b, h) + aoff + m * 2048 + k * 1024); } while (0)
; #define PG8_LDB(dst, b, h) do { _Pragma("unroll") for (int n = 0; n < 2; ++n) _Pragma("unroll") for (int k = 0; k < 2; ++k) dst[n][k] = *(const PG8_LAS bf16x8*)(lds + PG8_SB(b, h) + boff + n * 2048 + k * 1024); } while (0)
; #define PG8_MMA(ai, bj, At, Bt) do { __builtin_amdgcn_s_setprio(1); _Pragma("unroll") for (int m = 0; m < 4; ++m) _Pragma("unroll") for (int n = 0; n < 2; ++n) _Pragma("unroll") for (int k = 0; k < 2; ++k) \
;         acc[ai][bj][m][n] = __builtin_amdgcn_mfma_f32_16x16x32_bf16(Bt[n][k], At[m][k], acc[ai][bj][m][n], 0, 0, 0); __builtin_amdgcn_s_setprio(0); } while (0)
; #define PG8_WAIT_V(n) asm volatile("s_waitcnt vmcnt(" #n ")" ::: "memory")
; #define PG8_WAIT_L(n) asm volatile("s_waitcnt lgkmcnt(" #n ")" ::: "memory")
; #define PG8_BAR __builtin_amdgcn_s_barrier()
; template <class Epi, class Sched, bool ALIGN_EPI = false, bool SP2 = false>
; __device__ __forceinline__ void gemm_phase(PG8_LAS unsigned char* lds, const Gemm g, const Sched& S, const Epi& E) {
;     ...
;             const char* a1 = cA + (size_t)(t + 1) * kstep;
;             const char* a2 = last ? nA : cA + (size_t)(t + 2) * kstep; const char* b2 = last ? nB : cB + (size_t)(t + 2) * kstep;
;             const char* a3 = a2 + kstep; const char* b3 = b2 + kstep;
;             if (last && has_next) S.a_ready(nxt);
;             if constexpr (SP2) {
;             PG8_LDB(B0, 0, 0); PG8_LDB(B1, 0, 1); PG8_SCHED; PG8_LDA(At, 0, 0); PG8_STAGE(PG8_SA(1, 1), a1 + hstep, voffA);
;             PG8_WAIT_V(8); PG8_WAIT_L(0); PG8_BAR; PG8_MMA(0, 0, At, B0); PG8_MMA(0, 1, At, B1); PG8_BAR; PG8_SCHED;
;             PG8_LDA(At, 0, 1); PG8_STAGE(PG8_SB(0, 0), b2, voffB); PG8_STAGE(PG8_SB(0, 1), b2 + hstep, voffB); PG8_STAGE(PG8_SA(0, 0), a2, voffA);
;             PG8_WAIT_V(8); PG8_WAIT_L(0); PG8_BAR; PG8_MMA(1, 0, At, B0); PG8_MMA(1, 1, At, B1); PG8_BAR; PG8_SCHED;
.LBB0_100:
	s_add_u32 s28, s8, 0xfffc0080
	s_addc_u32 s29, s9, -1
	s_cmp_eq_u32 s45, 12
	s_cselect_b32 s31, s3, s29
	s_cselect_b32 s30, s7, s28
	s_cselect_b32 s29, s11, s44
	s_cselect_b32 s28, s21, s23
	ds_read_b128 v[132:135], v204
	ds_read_b128 v[136:139], v204 offset:1024
	ds_read_b128 v[140:143], v204 offset:2048
	ds_read_b128 v[144:147], v204 offset:3072
	ds_read_b128 v[148:151], v204 offset:16384
	ds_read_b128 v[152:155], v204 offset:17408
	ds_read_b128 v[156:159], v204 offset:18432
	ds_read_b128 v[160:163], v204 offset:19456
	v_lshl_add_u64 v[194:195], s[8:9], 0, v[178:179]
	s_add_i32 m0, s42, 0xc000
	ds_read_b128 v[164:167], v205
	ds_read_b128 v[182:185], v205 offset:1024
	ds_read_b128 v[186:189], v205 offset:2048
	ds_read_b128 v[190:193], v205 offset:3072
	ds_read_b128 v[208:211], v205 offset:4096
	ds_read_b128 v[212:215], v205 offset:5120
	ds_read_b128 v[216:219], v205 offset:6144
	ds_read_b128 v[220:223], v205 offset:7168
	global_load_lds_dwordx4 v[194:195], off
	s_add_i32 m0, s42, 0xe000
	v_lshl_add_u64 v[194:195], s[8:9], 0, v[180:181]
	global_load_lds_dwordx4 v[194:195], off
	s_waitcnt vmcnt(8) lgkmcnt(0)
	s_barrier
	s_setprio 1
	v_mfma_f32_16x16x32_bf16 v[128:131], v[132:135], v[164:167], v[128:131]
	v_mfma_f32_16x16x32_bf16 v[124:127], v[140:143], v[164:167], v[124:127]
	v_mfma_f32_16x16x32_bf16 v[112:115], v[132:135], v[186:189], v[112:115]
	v_mfma_f32_16x16x32_bf16 v[108:111], v[140:143], v[186:189], v[108:111]
	v_mfma_f32_16x16x32_bf16 v[96:99], v[132:135], v[208:211], v[96:99]
	v_mfma_f32_16x16x32_bf16 v[92:95], v[140:143], v[208:211], v[92:95]
	v_mfma_f32_16x16x32_bf16 v[80:83], v[132:135], v[216:219], v[80:83]
	v_mfma_f32_16x16x32_bf16 v[76:79], v[140:143], v[216:219], v[76:79]
	v_mfma_f32_16x16x32_bf16 v[128:131], v[136:139], v[182:185], v[128:131]
	v_mfma_f32_16x16x32_bf16 v[124:127], v[144:147], v[182:185], v[124:127]
	v_mfma_f32_16x16x32_bf16 v[112:115], v[136:139], v[190:193], v[112:115]
	v_mfma_f32_16x16x32_bf16 v[108:111], v[144:147], v[190:193], v[108:111]
	v_mfma_f32_16x16x32_bf16 v[96:99], v[136:139], v[212:215], v[96:99]
	v_mfma_f32_16x16x32_bf16 v[92:95], v[144:147], v[212:215], v[92:95]
	v_mfma_f32_16x16x32_bf16 v[80:83], v[136:139], v[220:223], v[80:83]
	v_mfma_f32_16x16x32_bf16 v[76:79], v[144:147], v[220:223], v[76:79]
	s_setprio 0
	s_setprio 1
	v_mfma_f32_16x16x32_bf16 v[120:123], v[148:151], v[164:167], v[120:123]
	v_mfma_f32_16x16x32_bf16 v[116:119], v[156:159], v[164:167], v[116:119]
	v_mfma_f32_16x16x32_bf16 v[104:107], v[148:151], v[186:189], v[104:107]
	v_mfma_f32_16x16x32_bf16 v[100:103], v[156:159], v[186:189], v[100:103]
	v_mfma_f32_16x16x32_bf16 v[88:91], v[148:151], v[208:211], v[88:91]
	v_mfma_f32_16x16x32_bf16 v[84:87], v[156:159], v[208:211], v[84:87]
	v_mfma_f32_16x16x32_bf16 v[72:75], v[148:151], v[216:219], v[72:75]
	v_mfma_f32_16x16x32_bf16 v[68:71], v[156:159], v[216:219], v[68:71]
	v_mfma_f32_16x16x32_bf16 v[120:123], v[152:155], v[182:185], v[120:123]
	v_mfma_f32_16x16x32_bf16 v[116:119], v[160:163], v[182:185], v[116:119]
	v_mfma_f32_16x16x32_bf16 v[104:107], v[152:155], v[190:193], v[104:107]
	v_mfma_f32_16x16x32_bf16 v[100:103], v[160:163], v[190:193], v[100:103]
	v_mfma_f32_16x16x32_bf16 v[88:91], v[152:155], v[212:215], v[88:91]
	v_mfma_f32_16x16x32_bf16 v[84:87], v[160:163], v[212:215], v[84:87]
	v_mfma_f32_16x16x32_bf16 v[72:75], v[152:155], v[220:223], v[72:75]
	v_mfma_f32_16x16x32_bf16 v[68:71], v[160:163], v[220:223], v[68:71]
	s_setprio 0
	s_barrier
	v_lshl_add_u64 v[194:195], s[28:29], 0, v[168:169]
	s_add_i32 m0, s41, 0x10000
	ds_read_b128 v[164:167], v205 offset:16384
	ds_read_b128 v[182:185], v205 offset:17408
	ds_read_b128 v[186:189], v205 offset:18432
	ds_read_b128 v[190:193], v205 offset:19456
	ds_read_b128 v[208:211], v205 offset:20480
	ds_read_b128 v[212:215], v205 offset:21504
	ds_read_b128 v[216:219], v205 offset:22528
	ds_read_b128 v[220:223], v205 offset:23552
	global_load_lds_dwordx4 v[194:195], off
	s_add_i32 m0, s41, 0x12000
	s_add_u32 s54, s28, 0x40000
	v_lshl_add_u64 v[202:203], s[28:29], 0, v[172:173]
	s_addc_u32 s55, s29, 0
	global_load_lds_dwordx4 v[202:203], off
	v_lshl_add_u64 v[224:225], s[54:55], 0, v[168:169]
	s_add_i32 m0, s41, 0x14000
	v_lshl_add_u64 v[226:227], s[30:31], 0, v[170:171]
	global_load_lds_dwordx4 v[224:225], off
	s_add_i32 m0, s41, 0x16000
	v_lshl_add_u64 v[224:225], s[54:55], 0, v[172:173]
	global_load_lds_dwordx4 v[224:225], off
	s_mov_b32 m0, s42
	v_lshl_add_u64 v[224:225], s[30:31], 0, v[0:1]
	global_load_lds_dwordx4 v[224:225], off
	s_mov_b32 m0, s43
	s_add_i32 s53, 0, 0x18000
	global_load_lds_dwordx4 v[226:227], off
	s_waitcnt vmcnt(8) lgkmcnt(0)
	s_barrier
; #define PG8_STAGE(bufoff, gbase, voff) do { _Pragma("unroll") for (int _i = 0; _i < 2; ++_i) \
;         __builtin_amdgcn_global_load_lds((const unsigned*)((const char*)(gbase) + (voff)[_i]), (PG8_LAS unsigned*)(lds + (bufoff) + ldsw + _i * 8192), 16, 0, 0); } while (0)
; #define PG8_LDA(dst, b, h) do { _Pragma("unroll") for (int m = 0; m < 4; ++m) _Pragma("unroll") for (int k = 0; k < 2; ++k) dst[m][k] = *(const PG8_LAS bf16x8*)(lds + PG8_SA(b, h) + aoff + m * 2048 + k * 1024); } while (0)
; #define PG8_LDB(dst, b, h) do { _Pragma("unroll") for (int n = 0; n < 2; ++n) _Pragma("unroll") for (int k = 0; k < 2; ++k) dst[n][k] = *(const PG8_LAS bf16x8*)(lds + PG8_SB(b, h) + boff + n * 2048 + k * 1024); } while (0)
; #define PG8_MMA(ai, bj, At, Bt) do { __builtin_amdgcn_s_setprio(1); _Pragma("unroll") for (int m = 0; m < 4; ++m) _Pragma("unroll") for (int n = 0; n < 2; ++n) _Pragma("unroll") for (int k = 0; k < 2; ++k) \
;         acc[ai][bj][m][n] = __builtin_amdgcn_mfma_f32_16x16x32_bf16(Bt[n][k], At[m][k], acc[ai][bj][m][n], 0, 0, 0); __builtin_amdgcn_s_setprio(0); } while (0)
; #define PG8_WAIT_V(n) asm volatile("s_waitcnt vmcnt(" #n ")" ::: "memory")
; #define PG8_WAIT_L(n) asm volatile("s_waitcnt lgkmcnt(" #n ")" ::: "memory")
; #define PG8_BAR __builtin_amdgcn_s_barrier()
; #define PG8_SCHED __builtin_amdgcn_sched_barrier(0)
; template <class Epi, class Sched, bool ALIGN_EPI = false, bool SP2 = false>
; __device__ __forceinline__ void gemm_phase(PG8_LAS unsigned char* lds, const Gemm g, const Sched& S, const Epi& E) {
;     ...
;             PG8_WAIT_V(8); PG8_WAIT_L(0); PG8_BAR; PG8_MMA(1, 0, At, B0); PG8_MMA(1, 1, At, B1); PG8_BAR; PG8_SCHED;
;             PG8_LDB(B0, 1, 0); PG8_LDB(B1, 1, 1); PG8_SCHED; PG8_LDA(At, 1, 0); PG8_STAGE(PG8_SA(0, 1), a2 + hstep, voffA);
;             PG8_WAIT_V(8); PG8_WAIT_L(0); PG8_BAR; PG8_MMA(0, 0, At, B0); PG8_MMA(0, 1, At, B1); PG8_BAR; PG8_SCHED;
	s_setprio 1
	v_mfma_f32_16x16x32_bf16 v[64:67], v[132:135], v[164:167], v[64:67]
	v_mfma_f32_16x16x32_bf16 v[60:63], v[140:143], v[164:167], v[60:63]
	v_mfma_f32_16x16x32_bf16 v[48:51], v[132:135], v[186:189], v[48:51]
	v_mfma_f32_16x16x32_bf16 v[44:47], v[140:143], v[186:189], v[44:47]
	v_mfma_f32_16x16x32_bf16 v[32:35], v[132:135], v[208:211], v[32:35]
	v_mfma_f32_16x16x32_bf16 v[28:31], v[140:143], v[208:211], v[28:31]
	v_mfma_f32_16x16x32_bf16 v[16:19], v[132:135], v[216:219], v[16:19]
	v_mfma_f32_16x16x32_bf16 v[12:15], v[140:143], v[216:219], v[12:15]
	v_mfma_f32_16x16x32_bf16 v[64:67], v[136:139], v[182:185], v[64:67]
	v_mfma_f32_16x16x32_bf16 v[60:63], v[144:147], v[182:185], v[60:63]
	v_mfma_f32_16x16x32_bf16 v[48:51], v[136:139], v[190:193], v[48:51]
	v_mfma_f32_16x16x32_bf16 v[44:47], v[144:147], v[190:193], v[44:47]
	v_mfma_f32_16x16x32_bf16 v[32:35], v[136:139], v[212:215], v[32:35]
	v_mfma_f32_16x16x32_bf16 v[28:31], v[144:147], v[212:215], v[28:31]
	v_mfma_f32_16x16x32_bf16 v[16:19], v[136:139], v[220:223], v[16:19]
	v_mfma_f32_16x16x32_bf16 v[12:15], v[144:147], v[220:223], v[12:15]
	s_setprio 0
	s_setprio 1
	v_mfma_f32_16x16x32_bf16 v[56:59], v[148:151], v[164:167], v[56:59]
	v_mfma_f32_16x16x32_bf16 v[52:55], v[156:159], v[164:167], v[52:55]
	v_mfma_f32_16x16x32_bf16 v[40:43], v[148:151], v[186:189], v[40:43]
	v_mfma_f32_16x16x32_bf16 v[36:39], v[156:159], v[186:189], v[36:39]
	v_mfma_f32_16x16x32_bf16 v[24:27], v[148:151], v[208:211], v[24:27]
	v_mfma_f32_16x16x32_bf16 v[20:23], v[156:159], v[208:211], v[20:23]
	v_mfma_f32_16x16x32_bf16 v[8:11], v[148:151], v[216:219], v[8:11]
	v_mfma_f32_16x16x32_bf16 v[4:7], v[156:159], v[216:219], v[4:7]
	v_mfma_f32_16x16x32_bf16 v[56:59], v[152:155], v[182:185], v[56:59]
	v_mfma_f32_16x16x32_bf16 v[52:55], v[160:163], v[182:185], v[52:55]
	v_mfma_f32_16x16x32_bf16 v[40:43], v[152:155], v[190:193], v[40:43]
	v_mfma_f32_16x16x32_bf16 v[36:39], v[160:163], v[190:193], v[36:39]
	v_mfma_f32_16x16x32_bf16 v[24:27], v[152:155], v[212:215], v[24:27]
	v_mfma_f32_16x16x32_bf16 v[20:23], v[160:163], v[212:215], v[20:23]
	v_mfma_f32_16x16x32_bf16 v[8:11], v[152:155], v[220:223], v[8:11]
	v_mfma_f32_16x16x32_bf16 v[4:7], v[160:163], v[220:223], v[4:7]
	s_setprio 0
	s_barrier
	ds_read_b128 v[132:135], v204 offset:32768
	ds_read_b128 v[136:139], v204 offset:33792
	ds_read_b128 v[140:143], v204 offset:34816
	ds_read_b128 v[144:147], v204 offset:35840
	ds_read_b128 v[148:151], v204 offset:49152
	ds_read_b128 v[152:155], v204 offset:50176
	ds_read_b128 v[156:159], v204 offset:51200
	ds_read_b128 v[160:163], v204 offset:52224
	s_add_u32 s30, s30, 0x40000
	s_addc_u32 s31, s31, 0
	s_mov_b32 m0, s46
	v_lshl_add_u64 v[228:229], s[30:31], 0, v[0:1]
	ds_read_b128 v[164:167], v205 offset:32768
	ds_read_b128 v[182:185], v205 offset:33792
	ds_read_b128 v[186:189], v205 offset:34816
	ds_read_b128 v[190:193], v205 offset:35840
	ds_read_b128 v[208:211], v205 offset:36864
	ds_read_b128 v[212:215], v205 offset:37888
	ds_read_b128 v[216:219], v205 offset:38912
	ds_read_b128 v[220:223], v205 offset:39936
	global_load_lds_dwordx4 v[228:229], off
	s_mov_b32 m0, s47
	v_lshl_add_u64 v[228:229], s[30:31], 0, v[170:171]
	global_load_lds_dwordx4 v[228:229], off
	s_waitcnt vmcnt(8) lgkmcnt(0)
	s_barrier
	s_setprio 1
	v_mfma_f32_16x16x32_bf16 v[128:131], v[132:135], v[164:167], v[128:131]
	v_mfma_f32_16x16x32_bf16 v[124:127], v[140:143], v[164:167], v[124:127]
	v_mfma_f32_16x16x32_bf16 v[112:115], v[132:135], v[186:189], v[112:115]
	v_mfma_f32_16x16x32_bf16 v[108:111], v[140:143], v[186:189], v[108:111]
	v_mfma_f32_16x16x32_bf16 v[96:99], v[132:135], v[208:211], v[96:99]
	v_mfma_f32_16x16x32_bf16 v[92:95], v[140:143], v[208:211], v[92:95]
	v_mfma_f32_16x16x32_bf16 v[80:83], v[132:135], v[216:219], v[80:83]
	v_mfma_f32_16x16x32_bf16 v[76:79], v[140:143], v[216:219], v[76:79]
	v_mfma_f32_16x16x32_bf16 v[128:131], v[136:139], v[182:185], v[128:131]
	v_mfma_f32_16x16x32_bf16 v[124:127], v[144:147], v[182:185], v[124:127]
	v_mfma_f32_16x16x32_bf16 v[112:115], v[136:139], v[190:193], v[112:115]
	v_mfma_f32_16x16x32_bf16 v[108:111], v[144:147], v[190:193], v[108:111]
	v_mfma_f32_16x16x32_bf16 v[96:99], v[136:139], v[212:215], v[96:99]
	v_mfma_f32_16x16x32_bf16 v[92:95], v[144:147], v[212:215], v[92:95]
	v_mfma_f32_16x16x32_bf16 v[80:83], v[136:139], v[220:223], v[80:83]
	v_mfma_f32_16x16x32_bf16 v[76:79], v[144:147], v[220:223], v[76:79]
	s_setprio 0
	s_setprio 1
	v_mfma_f32_16x16x32_bf16 v[120:123], v[148:151], v[164:167], v[120:123]
	v_mfma_f32_16x16x32_bf16 v[116:119], v[156:159], v[164:167], v[116:119]
	v_mfma_f32_16x16x32_bf16 v[104:107], v[148:151], v[186:189], v[104:107]
	v_mfma_f32_16x16x32_bf16 v[100:103], v[156:159], v[186:189], v[100:103]
	v_mfma_f32_16x16x32_bf16 v[88:91], v[148:151], v[208:211], v[88:91]
	v_mfma_f32_16x16x32_bf16 v[84:87], v[156:159], v[208:211], v[84:87]
	v_mfma_f32_16x16x32_bf16 v[72:75], v[148:151], v[216:219], v[72:75]
	v_mfma_f32_16x16x32_bf16 v[68:71], v[156:159], v[216:219], v[68:71]
	v_mfma_f32_16x16x32_bf16 v[120:123], v[152:155], v[182:185], v[120:123]
	v_mfma_f32_16x16x32_bf16 v[116:119], v[160:163], v[182:185], v[116:119]
	v_mfma_f32_16x16x32_bf16 v[104:107], v[152:155], v[190:193], v[104:107]
	v_mfma_f32_16x16x32_bf16 v[100:103], v[160:163], v[190:193], v[100:103]
	v_mfma_f32_16x16x32_bf16 v[88:91], v[152:155], v[212:215], v[88:91]
	v_mfma_f32_16x16x32_bf16 v[84:87], v[160:163], v[212:215], v[84:87]
	v_mfma_f32_16x16x32_bf16 v[72:75], v[152:155], v[220:223], v[72:75]
	v_mfma_f32_16x16x32_bf16 v[68:71], v[160:163], v[220:223], v[68:71]
	s_setprio 0
	s_barrier
; #define PG8_STAGE(bufoff, gbase, voff) do { _Pragma("unroll") for (int _i = 0; _i < 2; ++_i) \
;         __builtin_amdgcn_global_load_lds((const unsigned*)((const char*)(gbase) + (voff)[_i]), (PG8_LAS unsigned*)(lds + (bufoff) + ldsw + _i * 8192), 16, 0, 0); } while (0)
; #define PG8_LDA(dst, b, h) do { _Pragma("unroll") for (int m = 0; m < 4; ++m) _Pragma("unroll") for (int k = 0; k < 2; ++k) dst[m][k] = *(const PG8_LAS bf16x8*)(lds + PG8_SA(b, h) + aoff + m * 2048 + k * 1024); } while (0)
; #define PG8_MMA(ai, bj, At, Bt) do { __builtin_amdgcn_s_setprio(1); _Pragma("unroll") for (int m = 0; m < 4; ++m) _Pragma("unroll") for (int n = 0; n < 2; ++n) _Pragma("unroll") for (int k = 0; k < 2; ++k) \
;         acc[ai][bj][m][n] = __builtin_amdgcn_mfma_f32_16x16x32_bf16(Bt[n][k], At[m][k], acc[ai][bj][m][n], 0, 0, 0); __builtin_amdgcn_s_setprio(0); } while (0)
; #define PG8_WAIT_V(n) asm volatile("s_waitcnt vmcnt(" #n ")" ::: "memory")
; #define PG8_WAIT_L(n) asm volatile("s_waitcnt lgkmcnt(" #n ")" ::: "memory")
; #define PG8_BAR __builtin_amdgcn_s_barrier()
; #define PG8_SCHED __builtin_amdgcn_sched_barrier(0)
; template <class Epi, class Sched, bool ALIGN_EPI = false, bool SP2 = false>
; __device__ __forceinline__ void gemm_phase(PG8_LAS unsigned char* lds, const Gemm g, const Sched& S, const Epi& E) {
;     ...
;         for (int t = 0; t < nt; t += 2) {
;             const bool last = (t == nt - 2);
;             const char* a1 = cA + (size_t)(t + 1) * kstep;
;             const char* a2 = last ? nA : cA + (size_t)(t + 2) * kstep; const char* b2 = last ? nB : cB + (size_t)(t + 2) * kstep;
;             const char* a3 = a2 + kstep; const char* b3 = b2 + kstep;
;             if (last && has_next) S.a_ready(nxt);
;     ...
;             PG8_LDA(At, 1, 1); PG8_STAGE(PG8_SB(1, 0), b3, voffB); PG8_STAGE(PG8_SB(1, 1), b3 + hstep, voffB); PG8_STAGE(PG8_SA(1, 0), a3, voffA);
;             PG8_WAIT_V(8); PG8_WAIT_L(0); PG8_BAR; PG8_MMA(1, 0, At, B0); PG8_MMA(1, 1, At, B1); PG8_BAR; PG8_SCHED;
	s_add_i32 m0, s41, 0x17f80
	ds_read_b128 v[164:167], v205 offset:49152
	ds_read_b128 v[182:185], v205 offset:50176
	ds_read_b128 v[186:189], v205 offset:51200
	ds_read_b128 v[190:193], v205 offset:52224
	ds_read_b128 v[208:211], v205 offset:53248
	ds_read_b128 v[212:215], v205 offset:54272
	ds_read_b128 v[216:219], v205 offset:55296
	ds_read_b128 v[220:223], v205 offset:56320
	global_load_lds_dwordx4 v[194:195], off offset:128
	s_add_i32 m0, s41, 0x19f80
	s_add_u32 s28, s28, 0x40080
	s_addc_u32 s29, s29, 0
	global_load_lds_dwordx4 v[202:203], off offset:128
	s_add_i32 m0, s41, 0x1c000
	v_lshl_add_u64 v[194:195], s[28:29], 0, v[168:169]
	global_load_lds_dwordx4 v[194:195], off
	s_add_i32 m0, s41, 0x1e000
	v_lshl_add_u64 v[194:195], s[28:29], 0, v[172:173]
	global_load_lds_dwordx4 v[194:195], off
	s_add_i32 m0, s50, 0xffffff80
	s_add_u32 s8, s8, 0x100
	s_addc_u32 s9, s9, 0
	global_load_lds_dwordx4 v[224:225], off offset:128
	s_add_i32 m0, s51, 0xffffff80
	s_add_u32 s23, s23, 0x100
	s_addc_u32 s44, s44, 0
	global_load_lds_dwordx4 v[226:227], off offset:128
	s_waitcnt vmcnt(8) lgkmcnt(0)
	s_barrier
	s_setprio 1
	v_mfma_f32_16x16x32_bf16 v[64:67], v[132:135], v[164:167], v[64:67]
	v_mfma_f32_16x16x32_bf16 v[60:63], v[140:143], v[164:167], v[60:63]
	v_mfma_f32_16x16x32_bf16 v[48:51], v[132:135], v[186:189], v[48:51]
	v_mfma_f32_16x16x32_bf16 v[44:47], v[140:143], v[186:189], v[44:47]
	v_mfma_f32_16x16x32_bf16 v[32:35], v[132:135], v[208:211], v[32:35]
	v_mfma_f32_16x16x32_bf16 v[28:31], v[140:143], v[208:211], v[28:31]
	v_mfma_f32_16x16x32_bf16 v[16:19], v[132:135], v[216:219], v[16:19]
	v_mfma_f32_16x16x32_bf16 v[12:15], v[140:143], v[216:219], v[12:15]
	v_mfma_f32_16x16x32_bf16 v[64:67], v[136:139], v[182:185], v[64:67]
	v_mfma_f32_16x16x32_bf16 v[60:63], v[144:147], v[182:185], v[60:63]
	v_mfma_f32_16x16x32_bf16 v[48:51], v[136:139], v[190:193], v[48:51]
	v_mfma_f32_16x16x32_bf16 v[44:47], v[144:147], v[190:193], v[44:47]
	v_mfma_f32_16x16x32_bf16 v[32:35], v[136:139], v[212:215], v[32:35]
	v_mfma_f32_16x16x32_bf16 v[28:31], v[144:147], v[212:215], v[28:31]
	v_mfma_f32_16x16x32_bf16 v[16:19], v[136:139], v[220:223], v[16:19]
	v_mfma_f32_16x16x32_bf16 v[12:15], v[144:147], v[220:223], v[12:15]
	s_setprio 0
	s_setprio 1
	v_mfma_f32_16x16x32_bf16 v[56:59], v[148:151], v[164:167], v[56:59]
	v_mfma_f32_16x16x32_bf16 v[52:55], v[156:159], v[164:167], v[52:55]
	v_mfma_f32_16x16x32_bf16 v[40:43], v[148:151], v[186:189], v[40:43]
	v_mfma_f32_16x16x32_bf16 v[36:39], v[156:159], v[186:189], v[36:39]
	v_mfma_f32_16x16x32_bf16 v[24:27], v[148:151], v[208:211], v[24:27]
	v_mfma_f32_16x16x32_bf16 v[20:23], v[156:159], v[208:211], v[20:23]
	v_mfma_f32_16x16x32_bf16 v[8:11], v[148:151], v[216:219], v[8:11]
	v_mfma_f32_16x16x32_bf16 v[4:7], v[156:159], v[216:219], v[4:7]
	v_mfma_f32_16x16x32_bf16 v[56:59], v[152:155], v[182:185], v[56:59]
	v_mfma_f32_16x16x32_bf16 v[52:55], v[160:163], v[182:185], v[52:55]
	v_mfma_f32_16x16x32_bf16 v[40:43], v[152:155], v[190:193], v[40:43]
	v_mfma_f32_16x16x32_bf16 v[36:39], v[160:163], v[190:193], v[36:39]
	v_mfma_f32_16x16x32_bf16 v[24:27], v[152:155], v[212:215], v[24:27]
	v_mfma_f32_16x16x32_bf16 v[20:23], v[160:163], v[212:215], v[20:23]
	v_mfma_f32_16x16x32_bf16 v[8:11], v[152:155], v[220:223], v[8:11]
	v_mfma_f32_16x16x32_bf16 v[4:7], v[160:163], v[220:223], v[4:7]
	s_setprio 0
	s_barrier
	s_add_i32 s45, s45, 2
	s_cmp_gt_u32 s45, 13
	s_cbranch_scc0 .LBB0_100
	s_and_b64 vcc, exec, s[14:15]
	s_cbranch_vccz .LBB0_103
	s_barrier

; #define PG8_STAGE(bufoff, gbase, voff) do { _Pragma("unroll") for (int _i = 0; _i < 2; ++_i) \
;         __builtin_amdgcn_global_load_lds((const unsigned*)((const char*)(gbase) + (voff)[_i]), (PG8_LAS unsigned*)(lds + (bufoff) + ldsw + _i * 8192), 16, 0, 0); } while (0)
; #define PG8_LDA(dst, b, h) do { _Pragma("unroll") for (int m = 0; m < 4; ++m) _Pragma("unroll") for (int k = 0; k < 2; ++k) dst[m][k] = *(const PG8_LAS bf16x8*)(lds + PG8_SA(b, h) + aoff + m * 2048 + k * 1024); } while (0)
; #define PG8_LDB(dst, b, h) do { _Pragma("unroll") for (int n = 0; n < 2; ++n) _Pragma("unroll") for (int k = 0; k < 2; ++k) dst[n][k] = *(const PG8_LAS bf16x8*)(lds + PG8_SB(b, h) + boff + n * 2048 + k * 1024); } while (0)
; #define PG8_MMA(ai, bj, At, Bt) do { __builtin_amdgcn_s_setprio(1); _Pragma("unroll") for (int m = 0; m < 4; ++m) _Pragma("unroll") for (int n = 0; n < 2; ++n) _Pragma("unroll") for (int k = 0; k < 2; ++k) \
;         acc[ai][bj][m][n] = __builtin_amdgcn_mfma_f32_16x16x32_bf16(Bt[n][k], At[m][k], acc[ai][bj][m][n], 0, 0, 0); __builtin_amdgcn_s_setprio(0); } while (0)
; #define PG8_WAIT_V(n) asm volatile("s_waitcnt vmcnt(" #n ")" ::: "memory")
; #define PG8_WAIT_L(n) asm volatile("s_waitcnt lgkmcnt(" #n ")" ::: "memory")
; #define PG8_BAR __builtin_amdgcn_s_barrier()
; template <class Epi, class Sched, bool ALIGN_EPI = false, bool SP2 = false>
; __device__ __forceinline__ void gemm_phase(PG8_LAS unsigned char* lds, const Gemm g, const Sched& S, const Epi& E) {
;     ...
;             const char* a1 = cA + (size_t)(t + 1) * kstep;
;             const char* a2 = last ? nA : cA + (size_t)(t + 2) * kstep; const char* b2 = last ? nB : cB + (size_t)(t + 2) * kstep;
;             const char* a3 = a2 + kstep; const char* b3 = b2 + kstep;
;             if (last && has_next) S.a_ready(nxt);
;             if constexpr (SP2) {
;             PG8_LDB(B0, 0, 0); PG8_LDB(B1, 0, 1); PG8_SCHED; PG8_LDA(At, 0, 0); PG8_STAGE(PG8_SA(1, 1), a1 + hstep, voffA);
;             PG8_WAIT_V(8); PG8_WAIT_L(0); PG8_BAR; PG8_MMA(0, 0, At, B0); PG8_MMA(0, 1, At, B1); PG8_BAR; PG8_SCHED;
;             PG8_LDA(At, 0, 1); PG8_STAGE(PG8_SB(0, 0), b2, voffB); PG8_STAGE(PG8_SB(0, 1), b2 + hstep, voffB); PG8_STAGE(PG8_SA(0, 0), a2, voffA);
;             PG8_WAIT_V(8); PG8_WAIT_L(0); PG8_BAR; PG8_MMA(1, 0, At, B0); PG8_MMA(1, 1, At, B1); PG8_BAR; PG8_SCHED;
.LBB0_329:
	s_add_u32 s30, s28, 0xfffc0080
	s_addc_u32 s31, s29, -1
	s_cmp_eq_u32 s45, 12
	s_cselect_b32 s35, s3, s31
	s_cselect_b32 s34, s17, s30
	s_cselect_b32 s31, s19, s44
	s_cselect_b32 s30, s25, s27
	ds_read_b128 v[108:111], v251
	ds_read_b128 v[112:115], v251 offset:1024
	ds_read_b128 v[124:127], v251 offset:2048
	ds_read_b128 v[128:131], v251 offset:3072
	ds_read_b128 v[132:135], v251 offset:16384
	ds_read_b128 v[140:143], v251 offset:17408
	ds_read_b128 v[148:151], v251 offset:18432
	ds_read_b128 v[156:159], v251 offset:19456
	v_lshl_add_u64 v[212:213], s[28:29], 0, v[208:209]
	s_add_i32 m0, s42, 0xc000
	ds_read_b128 v[164:167], v253
	ds_read_b128 v[168:171], v253 offset:1024
	ds_read_b128 v[172:175], v253 offset:2048
	ds_read_b128 v[176:179], v253 offset:3072
	ds_read_b128 v[180:183], v253 offset:4096
	ds_read_b128 v[184:187], v253 offset:5120
	ds_read_b128 v[188:191], v253 offset:6144
	ds_read_b128 v[192:195], v253 offset:7168
	global_load_lds_dwordx4 v[212:213], off
	s_add_i32 m0, s42, 0xe000
	v_lshl_add_u64 v[212:213], s[28:29], 0, v[210:211]
	global_load_lds_dwordx4 v[212:213], off
	s_waitcnt vmcnt(8) lgkmcnt(0)
	s_barrier
	s_setprio 1
	v_mfma_f32_16x16x32_bf16 v[160:163], v[108:111], v[164:167], v[160:163]
	v_mfma_f32_16x16x32_bf16 v[152:155], v[124:127], v[164:167], v[152:155]
	v_mfma_f32_16x16x32_bf16 v[120:123], v[108:111], v[172:175], v[120:123]
	v_mfma_f32_16x16x32_bf16 v[116:119], v[124:127], v[172:175], v[116:119]
	v_mfma_f32_16x16x32_bf16 v[96:99], v[108:111], v[180:183], v[96:99]
	v_mfma_f32_16x16x32_bf16 v[92:95], v[124:127], v[180:183], v[92:95]
	v_mfma_f32_16x16x32_bf16 v[80:83], v[108:111], v[188:191], v[80:83]
	v_mfma_f32_16x16x32_bf16 v[76:79], v[124:127], v[188:191], v[76:79]
	v_mfma_f32_16x16x32_bf16 v[160:163], v[112:115], v[168:171], v[160:163]
	v_mfma_f32_16x16x32_bf16 v[152:155], v[128:131], v[168:171], v[152:155]
	v_mfma_f32_16x16x32_bf16 v[120:123], v[112:115], v[176:179], v[120:123]
	v_mfma_f32_16x16x32_bf16 v[116:119], v[128:131], v[176:179], v[116:119]
	v_mfma_f32_16x16x32_bf16 v[96:99], v[112:115], v[184:187], v[96:99]
	v_mfma_f32_16x16x32_bf16 v[92:95], v[128:131], v[184:187], v[92:95]
	v_mfma_f32_16x16x32_bf16 v[80:83], v[112:115], v[192:195], v[80:83]
	v_mfma_f32_16x16x32_bf16 v[76:79], v[128:131], v[192:195], v[76:79]
	s_setprio 0
	s_setprio 1
	v_mfma_f32_16x16x32_bf16 v[144:147], v[132:135], v[164:167], v[144:147]
	v_mfma_f32_16x16x32_bf16 v[136:139], v[148:151], v[164:167], v[136:139]
	v_mfma_f32_16x16x32_bf16 v[104:107], v[132:135], v[172:175], v[104:107]
	v_mfma_f32_16x16x32_bf16 v[100:103], v[148:151], v[172:175], v[100:103]
	v_mfma_f32_16x16x32_bf16 v[88:91], v[132:135], v[180:183], v[88:91]
	v_mfma_f32_16x16x32_bf16 v[84:87], v[148:151], v[180:183], v[84:87]
	v_mfma_f32_16x16x32_bf16 v[72:75], v[132:135], v[188:191], v[72:75]
	v_mfma_f32_16x16x32_bf16 v[68:71], v[148:151], v[188:191], v[68:71]
	v_mfma_f32_16x16x32_bf16 v[144:147], v[140:143], v[168:171], v[144:147]
	v_mfma_f32_16x16x32_bf16 v[136:139], v[156:159], v[168:171], v[136:139]
	v_mfma_f32_16x16x32_bf16 v[104:107], v[140:143], v[176:179], v[104:107]
	v_mfma_f32_16x16x32_bf16 v[100:103], v[156:159], v[176:179], v[100:103]
	v_mfma_f32_16x16x32_bf16 v[88:91], v[140:143], v[184:187], v[88:91]
	v_mfma_f32_16x16x32_bf16 v[84:87], v[156:159], v[184:187], v[84:87]
	v_mfma_f32_16x16x32_bf16 v[72:75], v[140:143], v[192:195], v[72:75]
	v_mfma_f32_16x16x32_bf16 v[68:71], v[156:159], v[192:195], v[68:71]
	s_setprio 0
	s_barrier
	v_lshl_add_u64 v[212:213], s[30:31], 0, v[202:203]
	s_add_i32 m0, s41, 0x10000
	ds_read_b128 v[164:167], v253 offset:16384
	ds_read_b128 v[168:171], v253 offset:17408
	ds_read_b128 v[172:175], v253 offset:18432
	ds_read_b128 v[176:179], v253 offset:19456
	ds_read_b128 v[180:183], v253 offset:20480
	ds_read_b128 v[184:187], v253 offset:21504
	ds_read_b128 v[188:191], v253 offset:22528
	ds_read_b128 v[192:195], v253 offset:23552
	global_load_lds_dwordx4 v[212:213], off
	s_add_i32 m0, s41, 0x12000
	s_add_u32 s52, s30, 0x40000
	v_lshl_add_u64 v[214:215], s[30:31], 0, v[206:207]
	s_addc_u32 s53, s31, 0
	global_load_lds_dwordx4 v[214:215], off
	v_lshl_add_u64 v[216:217], s[52:53], 0, v[202:203]
	s_add_i32 m0, s41, 0x14000
	v_lshl_add_u64 v[218:219], s[34:35], 0, v[204:205]
	global_load_lds_dwordx4 v[216:217], off
	s_add_i32 m0, s41, 0x16000
	v_lshl_add_u64 v[216:217], s[52:53], 0, v[206:207]
	global_load_lds_dwordx4 v[216:217], off
	s_mov_b32 m0, s42
	v_lshl_add_u64 v[216:217], s[34:35], 0, v[0:1]
	global_load_lds_dwordx4 v[216:217], off
	s_mov_b32 m0, s43
	s_add_i32 s52, 0, 0x18000
	global_load_lds_dwordx4 v[218:219], off
	s_waitcnt vmcnt(8) lgkmcnt(0)
	s_barrier
; #define PG8_STAGE(bufoff, gbase, voff) do { _Pragma("unroll") for (int _i = 0; _i < 2; ++_i) \
;         __builtin_amdgcn_global_load_lds((const unsigned*)((const char*)(gbase) + (voff)[_i]), (PG8_LAS unsigned*)(lds + (bufoff) + ldsw + _i * 8192), 16, 0, 0); } while (0)
; #define PG8_LDA(dst, b, h) do { _Pragma("unroll") for (int m = 0; m < 4; ++m) _Pragma("unroll") for (int k = 0; k < 2; ++k) dst[m][k] = *(const PG8_LAS bf16x8*)(lds + PG8_SA(b, h) + aoff + m * 2048 + k * 1024); } while (0)
; #define PG8_LDB(dst, b, h) do { _Pragma("unroll") for (int n = 0; n < 2; ++n) _Pragma("unroll") for (int k = 0; k < 2; ++k) dst[n][k] = *(const PG8_LAS bf16x8*)(lds + PG8_SB(b, h) + boff + n * 2048 + k * 1024); } while (0)
; #define PG8_MMA(ai, bj, At, Bt) do { __builtin_amdgcn_s_setprio(1); _Pragma("unroll") for (int m = 0; m < 4; ++m) _Pragma("unroll") for (int n = 0; n < 2; ++n) _Pragma("unroll") for (int k = 0; k < 2; ++k) \
;         acc[ai][bj][m][n] = __builtin_amdgcn_mfma_f32_16x16x32_bf16(Bt[n][k], At[m][k], acc[ai][bj][m][n], 0, 0, 0); __builtin_amdgcn_s_setprio(0); } while (0)
; #define PG8_WAIT_V(n) asm volatile("s_waitcnt vmcnt(" #n ")" ::: "memory")
; #define PG8_WAIT_L(n) asm volatile("s_waitcnt lgkmcnt(" #n ")" ::: "memory")
; #define PG8_BAR __builtin_amdgcn_s_barrier()
; #define PG8_SCHED __builtin_amdgcn_sched_barrier(0)
; template <class Epi, class Sched, bool ALIGN_EPI = false, bool SP2 = false>
; __device__ __forceinline__ void gemm_phase(PG8_LAS unsigned char* lds, const Gemm g, const Sched& S, const Epi& E) {
;     ...
;             PG8_WAIT_V(8); PG8_WAIT_L(0); PG8_BAR; PG8_MMA(1, 0, At, B0); PG8_MMA(1, 1, At, B1); PG8_BAR; PG8_SCHED;
;             PG8_LDB(B0, 1, 0); PG8_LDB(B1, 1, 1); PG8_SCHED; PG8_LDA(At, 1, 0); PG8_STAGE(PG8_SA(0, 1), a2 + hstep, voffA);
;             PG8_WAIT_V(8); PG8_WAIT_L(0); PG8_BAR; PG8_MMA(0, 0, At, B0); PG8_MMA(0, 1, At, B1); PG8_BAR; PG8_SCHED;
	s_setprio 1
	v_mfma_f32_16x16x32_bf16 v[64:67], v[108:111], v[164:167], v[64:67]
	v_mfma_f32_16x16x32_bf16 v[60:63], v[124:127], v[164:167], v[60:63]
	v_mfma_f32_16x16x32_bf16 v[48:51], v[108:111], v[172:175], v[48:51]
	v_mfma_f32_16x16x32_bf16 v[44:47], v[124:127], v[172:175], v[44:47]
	v_mfma_f32_16x16x32_bf16 v[32:35], v[108:111], v[180:183], v[32:35]
	v_mfma_f32_16x16x32_bf16 v[28:31], v[124:127], v[180:183], v[28:31]
	v_mfma_f32_16x16x32_bf16 v[16:19], v[108:111], v[188:191], v[16:19]
	v_mfma_f32_16x16x32_bf16 v[12:15], v[124:127], v[188:191], v[12:15]
	v_mfma_f32_16x16x32_bf16 v[64:67], v[112:115], v[168:171], v[64:67]
	v_mfma_f32_16x16x32_bf16 v[60:63], v[128:131], v[168:171], v[60:63]
	v_mfma_f32_16x16x32_bf16 v[48:51], v[112:115], v[176:179], v[48:51]
	v_mfma_f32_16x16x32_bf16 v[44:47], v[128:131], v[176:179], v[44:47]
	v_mfma_f32_16x16x32_bf16 v[32:35], v[112:115], v[184:187], v[32:35]
	v_mfma_f32_16x16x32_bf16 v[28:31], v[128:131], v[184:187], v[28:31]
	v_mfma_f32_16x16x32_bf16 v[16:19], v[112:115], v[192:195], v[16:19]
	v_mfma_f32_16x16x32_bf16 v[12:15], v[128:131], v[192:195], v[12:15]
	s_setprio 0
	s_setprio 1
	v_mfma_f32_16x16x32_bf16 v[56:59], v[132:135], v[164:167], v[56:59]
	v_mfma_f32_16x16x32_bf16 v[52:55], v[148:151], v[164:167], v[52:55]
	v_mfma_f32_16x16x32_bf16 v[40:43], v[132:135], v[172:175], v[40:43]
	v_mfma_f32_16x16x32_bf16 v[36:39], v[148:151], v[172:175], v[36:39]
	v_mfma_f32_16x16x32_bf16 v[24:27], v[132:135], v[180:183], v[24:27]
	v_mfma_f32_16x16x32_bf16 v[20:23], v[148:151], v[180:183], v[20:23]
	v_mfma_f32_16x16x32_bf16 v[8:11], v[132:135], v[188:191], v[8:11]
	v_mfma_f32_16x16x32_bf16 v[4:7], v[148:151], v[188:191], v[4:7]
	v_mfma_f32_16x16x32_bf16 v[56:59], v[140:143], v[168:171], v[56:59]
	v_mfma_f32_16x16x32_bf16 v[52:55], v[156:159], v[168:171], v[52:55]
	v_mfma_f32_16x16x32_bf16 v[40:43], v[140:143], v[176:179], v[40:43]
	v_mfma_f32_16x16x32_bf16 v[36:39], v[156:159], v[176:179], v[36:39]
	v_mfma_f32_16x16x32_bf16 v[24:27], v[140:143], v[184:187], v[24:27]
	v_mfma_f32_16x16x32_bf16 v[20:23], v[156:159], v[184:187], v[20:23]
	v_mfma_f32_16x16x32_bf16 v[8:11], v[140:143], v[192:195], v[8:11]
	v_mfma_f32_16x16x32_bf16 v[4:7], v[156:159], v[192:195], v[4:7]
	s_setprio 0
	s_barrier
	ds_read_b128 v[108:111], v251 offset:32768
	ds_read_b128 v[112:115], v251 offset:33792
	ds_read_b128 v[124:127], v251 offset:34816
	ds_read_b128 v[128:131], v251 offset:35840
	ds_read_b128 v[132:135], v251 offset:49152
	ds_read_b128 v[140:143], v251 offset:50176
	ds_read_b128 v[148:151], v251 offset:51200
	ds_read_b128 v[156:159], v251 offset:52224
	s_add_u32 s34, s34, 0x40000
	s_addc_u32 s35, s35, 0
	s_mov_b32 m0, s46
	v_lshl_add_u64 v[220:221], s[34:35], 0, v[0:1]
	ds_read_b128 v[164:167], v253 offset:32768
	ds_read_b128 v[168:171], v253 offset:33792
	ds_read_b128 v[172:175], v253 offset:34816
	ds_read_b128 v[176:179], v253 offset:35840
	ds_read_b128 v[180:183], v253 offset:36864
	ds_read_b128 v[184:187], v253 offset:37888
	ds_read_b128 v[188:191], v253 offset:38912
	ds_read_b128 v[192:195], v253 offset:39936
	global_load_lds_dwordx4 v[220:221], off
	s_mov_b32 m0, s47
	v_lshl_add_u64 v[220:221], s[34:35], 0, v[204:205]
	global_load_lds_dwordx4 v[220:221], off
	s_waitcnt vmcnt(8) lgkmcnt(0)
	s_barrier
	s_setprio 1
	v_mfma_f32_16x16x32_bf16 v[160:163], v[108:111], v[164:167], v[160:163]
	v_mfma_f32_16x16x32_bf16 v[152:155], v[124:127], v[164:167], v[152:155]
	v_mfma_f32_16x16x32_bf16 v[120:123], v[108:111], v[172:175], v[120:123]
	v_mfma_f32_16x16x32_bf16 v[116:119], v[124:127], v[172:175], v[116:119]
	v_mfma_f32_16x16x32_bf16 v[96:99], v[108:111], v[180:183], v[96:99]
	v_mfma_f32_16x16x32_bf16 v[92:95], v[124:127], v[180:183], v[92:95]
	v_mfma_f32_16x16x32_bf16 v[80:83], v[108:111], v[188:191], v[80:83]
	v_mfma_f32_16x16x32_bf16 v[76:79], v[124:127], v[188:191], v[76:79]
	v_mfma_f32_16x16x32_bf16 v[160:163], v[112:115], v[168:171], v[160:163]
	v_mfma_f32_16x16x32_bf16 v[152:155], v[128:131], v[168:171], v[152:155]
	v_mfma_f32_16x16x32_bf16 v[120:123], v[112:115], v[176:179], v[120:123]
	v_mfma_f32_16x16x32_bf16 v[116:119], v[128:131], v[176:179], v[116:119]
	v_mfma_f32_16x16x32_bf16 v[96:99], v[112:115], v[184:187], v[96:99]
	v_mfma_f32_16x16x32_bf16 v[92:95], v[128:131], v[184:187], v[92:95]
	v_mfma_f32_16x16x32_bf16 v[80:83], v[112:115], v[192:195], v[80:83]
	v_mfma_f32_16x16x32_bf16 v[76:79], v[128:131], v[192:195], v[76:79]
	s_setprio 0
	s_setprio 1
	v_mfma_f32_16x16x32_bf16 v[144:147], v[132:135], v[164:167], v[144:147]
	v_mfma_f32_16x16x32_bf16 v[136:139], v[148:151], v[164:167], v[136:139]
	v_mfma_f32_16x16x32_bf16 v[104:107], v[132:135], v[172:175], v[104:107]
	v_mfma_f32_16x16x32_bf16 v[100:103], v[148:151], v[172:175], v[100:103]
	v_mfma_f32_16x16x32_bf16 v[88:91], v[132:135], v[180:183], v[88:91]
	v_mfma_f32_16x16x32_bf16 v[84:87], v[148:151], v[180:183], v[84:87]
	v_mfma_f32_16x16x32_bf16 v[72:75], v[132:135], v[188:191], v[72:75]
	v_mfma_f32_16x16x32_bf16 v[68:71], v[148:151], v[188:191], v[68:71]
	v_mfma_f32_16x16x32_bf16 v[144:147], v[140:143], v[168:171], v[144:147]
	v_mfma_f32_16x16x32_bf16 v[136:139], v[156:159], v[168:171], v[136:139]
	v_mfma_f32_16x16x32_bf16 v[104:107], v[140:143], v[176:179], v[104:107]
	v_mfma_f32_16x16x32_bf16 v[100:103], v[156:159], v[176:179], v[100:103]
	v_mfma_f32_16x16x32_bf16 v[88:91], v[140:143], v[184:187], v[88:91]
	v_mfma_f32_16x16x32_bf16 v[84:87], v[156:159], v[184:187], v[84:87]
	v_mfma_f32_16x16x32_bf16 v[72:75], v[140:143], v[192:195], v[72:75]
	v_mfma_f32_16x16x32_bf16 v[68:71], v[156:159], v[192:195], v[68:71]
	s_setprio 0
	s_barrier
; #define PG8_STAGE(bufoff, gbase, voff) do { _Pragma("unroll") for (int _i = 0; _i < 2; ++_i) \
;         __builtin_amdgcn_global_load_lds((const unsigned*)((const char*)(gbase) + (voff)[_i]), (PG8_LAS unsigned*)(lds + (bufoff) + ldsw + _i * 8192), 16, 0, 0); } while (0)
; #define PG8_LDA(dst, b, h) do { _Pragma("unroll") for (int m = 0; m < 4; ++m) _Pragma("unroll") for (int k = 0; k < 2; ++k) dst[m][k] = *(const PG8_LAS bf16x8*)(lds + PG8_SA(b, h) + aoff + m * 2048 + k * 1024); } while (0)
; #define PG8_MMA(ai, bj, At, Bt) do { __builtin_amdgcn_s_setprio(1); _Pragma("unroll") for (int m = 0; m < 4; ++m) _Pragma("unroll") for (int n = 0; n < 2; ++n) _Pragma("unroll") for (int k = 0; k < 2; ++k) \
;         acc[ai][bj][m][n] = __builtin_amdgcn_mfma_f32_16x16x32_bf16(Bt[n][k], At[m][k], acc[ai][bj][m][n], 0, 0, 0); __builtin_amdgcn_s_setprio(0); } while (0)
; #define PG8_WAIT_V(n) asm volatile("s_waitcnt vmcnt(" #n ")" ::: "memory")
; #define PG8_WAIT_L(n) asm volatile("s_waitcnt lgkmcnt(" #n ")" ::: "memory")
; #define PG8_BAR __builtin_amdgcn_s_barrier()
; #define PG8_SCHED __builtin_amdgcn_sched_barrier(0)
; template <class Epi, class Sched, bool ALIGN_EPI = false, bool SP2 = false>
; __device__ __forceinline__ void gemm_phase(PG8_LAS unsigned char* lds, const Gemm g, const Sched& S, const Epi& E) {
;     ...
;         for (int t = 0; t < nt; t += 2) {
;             const bool last = (t == nt - 2);
;             const char* a1 = cA + (size_t)(t + 1) * kstep;
;             const char* a2 = last ? nA : cA + (size_t)(t + 2) * kstep; const char* b2 = last ? nB : cB + (size_t)(t + 2) * kstep;
;             const char* a3 = a2 + kstep; const char* b3 = b2 + kstep;
;             if (last && has_next) S.a_ready(nxt);
;     ...
;             PG8_LDA(At, 1, 1); PG8_STAGE(PG8_SB(1, 0), b3, voffB); PG8_STAGE(PG8_SB(1, 1), b3 + hstep, voffB); PG8_STAGE(PG8_SA(1, 0), a3, voffA);
;             PG8_WAIT_V(8); PG8_WAIT_L(0); PG8_BAR; PG8_MMA(1, 0, At, B0); PG8_MMA(1, 1, At, B1); PG8_BAR; PG8_SCHED;
	s_add_i32 m0, s41, 0x17f80
	ds_read_b128 v[164:167], v253 offset:49152
	ds_read_b128 v[168:171], v253 offset:50176
	ds_read_b128 v[172:175], v253 offset:51200
	ds_read_b128 v[176:179], v253 offset:52224
	ds_read_b128 v[180:183], v253 offset:53248
	ds_read_b128 v[184:187], v253 offset:54272
	ds_read_b128 v[188:191], v253 offset:55296
	ds_read_b128 v[192:195], v253 offset:56320
	global_load_lds_dwordx4 v[212:213], off offset:128
	s_add_i32 m0, s41, 0x19f80
	s_add_u32 s30, s30, 0x40080
	s_addc_u32 s31, s31, 0
	global_load_lds_dwordx4 v[214:215], off offset:128
	s_add_i32 m0, s41, 0x1c000
	v_lshl_add_u64 v[212:213], s[30:31], 0, v[202:203]
	global_load_lds_dwordx4 v[212:213], off
	s_add_i32 m0, s41, 0x1e000
	v_lshl_add_u64 v[212:213], s[30:31], 0, v[206:207]
	global_load_lds_dwordx4 v[212:213], off
	s_add_i32 m0, s49, 0xffffff80
	s_add_u32 s28, s28, 0x100
	s_addc_u32 s29, s29, 0
	global_load_lds_dwordx4 v[216:217], off offset:128
	s_add_i32 m0, s50, 0xffffff80
	s_add_u32 s27, s27, 0x100
	s_addc_u32 s44, s44, 0
	global_load_lds_dwordx4 v[218:219], off offset:128
	s_waitcnt vmcnt(8) lgkmcnt(0)
	s_barrier
	s_setprio 1
	v_mfma_f32_16x16x32_bf16 v[64:67], v[108:111], v[164:167], v[64:67]
	v_mfma_f32_16x16x32_bf16 v[60:63], v[124:127], v[164:167], v[60:63]
	v_mfma_f32_16x16x32_bf16 v[48:51], v[108:111], v[172:175], v[48:51]
	v_mfma_f32_16x16x32_bf16 v[44:47], v[124:127], v[172:175], v[44:47]
	v_mfma_f32_16x16x32_bf16 v[32:35], v[108:111], v[180:183], v[32:35]
	v_mfma_f32_16x16x32_bf16 v[28:31], v[124:127], v[180:183], v[28:31]
	v_mfma_f32_16x16x32_bf16 v[16:19], v[108:111], v[188:191], v[16:19]
	v_mfma_f32_16x16x32_bf16 v[12:15], v[124:127], v[188:191], v[12:15]
	v_mfma_f32_16x16x32_bf16 v[64:67], v[112:115], v[168:171], v[64:67]
	v_mfma_f32_16x16x32_bf16 v[60:63], v[128:131], v[168:171], v[60:63]
	v_mfma_f32_16x16x32_bf16 v[48:51], v[112:115], v[176:179], v[48:51]
	v_mfma_f32_16x16x32_bf16 v[44:47], v[128:131], v[176:179], v[44:47]
	v_mfma_f32_16x16x32_bf16 v[32:35], v[112:115], v[184:187], v[32:35]
	v_mfma_f32_16x16x32_bf16 v[28:31], v[128:131], v[184:187], v[28:31]
	v_mfma_f32_16x16x32_bf16 v[16:19], v[112:115], v[192:195], v[16:19]
	v_mfma_f32_16x16x32_bf16 v[12:15], v[128:131], v[192:195], v[12:15]
	s_setprio 0
	s_setprio 1
	v_mfma_f32_16x16x32_bf16 v[56:59], v[132:135], v[164:167], v[56:59]
	v_mfma_f32_16x16x32_bf16 v[52:55], v[148:151], v[164:167], v[52:55]
	v_mfma_f32_16x16x32_bf16 v[40:43], v[132:135], v[172:175], v[40:43]
	v_mfma_f32_16x16x32_bf16 v[36:39], v[148:151], v[172:175], v[36:39]
	v_mfma_f32_16x16x32_bf16 v[24:27], v[132:135], v[180:183], v[24:27]
	v_mfma_f32_16x16x32_bf16 v[20:23], v[148:151], v[180:183], v[20:23]
	v_mfma_f32_16x16x32_bf16 v[8:11], v[132:135], v[188:191], v[8:11]
	v_mfma_f32_16x16x32_bf16 v[4:7], v[148:151], v[188:191], v[4:7]
	v_mfma_f32_16x16x32_bf16 v[56:59], v[140:143], v[168:171], v[56:59]
	v_mfma_f32_16x16x32_bf16 v[52:55], v[156:159], v[168:171], v[52:55]
	v_mfma_f32_16x16x32_bf16 v[40:43], v[140:143], v[176:179], v[40:43]
	v_mfma_f32_16x16x32_bf16 v[36:39], v[156:159], v[176:179], v[36:39]
	v_mfma_f32_16x16x32_bf16 v[24:27], v[140:143], v[184:187], v[24:27]
	v_mfma_f32_16x16x32_bf16 v[20:23], v[156:159], v[184:187], v[20:23]
	v_mfma_f32_16x16x32_bf16 v[8:11], v[140:143], v[192:195], v[8:11]
	v_mfma_f32_16x16x32_bf16 v[4:7], v[156:159], v[192:195], v[4:7]
	s_setprio 0
	s_barrier
	s_add_i32 s45, s45, 2
	s_cmp_gt_u32 s45, 13
	s_cbranch_scc0 .LBB0_329
	s_and_b64 vcc, exec, s[14:15]
	s_cbranch_vccz .LBB0_332
	s_barrier

; #define PG8_STAGE(bufoff, gbase, voff) do { _Pragma("unroll") for (int _i = 0; _i < 2; ++_i) \
;         __builtin_amdgcn_global_load_lds((const unsigned*)((const char*)(gbase) + (voff)[_i]), (PG8_LAS unsigned*)(lds + (bufoff) + ldsw + _i * 8192), 16, 0, 0); } while (0)
; #define PG8_LDA(dst, b, h) do { _Pragma("unroll") for (int m = 0; m < 4; ++m) _Pragma("unroll") for (int k = 0; k < 2; ++k) dst[m][k] = *(const PG8_LAS bf16x8*)(lds + PG8_SA(b, h) + aoff + m * 2048 + k * 1024); } while (0)
; #define PG8_LDB(dst, b, h) do { _Pragma("unroll") for (int n = 0; n < 2; ++n) _Pragma("unroll") for (int k = 0; k < 2; ++k) dst[n][k] = *(const PG8_LAS bf16x8*)(lds + PG8_SB(b, h) + boff + n * 2048 + k * 1024); } while (0)
; #define PG8_MMA(ai, bj, At, Bt) do { __builtin_amdgcn_s_setprio(1); _Pragma("unroll") for (int m = 0; m < 4; ++m) _Pragma("unroll") for (int n = 0; n < 2; ++n) _Pragma("unroll") for (int k = 0; k < 2; ++k) \
;         acc[ai][bj][m][n] = __builtin_amdgcn_mfma_f32_16x16x32_bf16(Bt[n][k], At[m][k], acc[ai][bj][m][n], 0, 0, 0); __builtin_amdgcn_s_setprio(0); } while (0)
; #define PG8_WAIT_V(n) asm volatile("s_waitcnt vmcnt(" #n ")" ::: "memory")
; #define PG8_WAIT_L(n) asm volatile("s_waitcnt lgkmcnt(" #n ")" ::: "memory")
; #define PG8_BAR __builtin_amdgcn_s_barrier()
; template <class Epi, class Sched, bool ALIGN_EPI = false, bool SP2 = false>
; __device__ __forceinline__ void gemm_phase(PG8_LAS unsigned char* lds, const Gemm g, const Sched& S, const Epi& E) {
;     ...
;             const char* a1 = cA + (size_t)(t + 1) * kstep;
;             const char* a2 = last ? nA : cA + (size_t)(t + 2) * kstep; const char* b2 = last ? nB : cB + (size_t)(t + 2) * kstep;
;             const char* a3 = a2 + kstep; const char* b3 = b2 + kstep;
;             if (last && has_next) S.a_ready(nxt);
;             if constexpr (SP2) {
;             PG8_LDB(B0, 0, 0); PG8_LDB(B1, 0, 1); PG8_SCHED; PG8_LDA(At, 0, 0); PG8_STAGE(PG8_SA(1, 1), a1 + hstep, voffA);
;             PG8_WAIT_V(8); PG8_WAIT_L(0); PG8_BAR; PG8_MMA(0, 0, At, B0); PG8_MMA(0, 1, At, B1); PG8_BAR; PG8_SCHED;
;             PG8_LDA(At, 0, 1); PG8_STAGE(PG8_SB(0, 0), b2, voffB); PG8_STAGE(PG8_SB(0, 1), b2 + hstep, voffB); PG8_STAGE(PG8_SA(0, 0), a2, voffA);
;             PG8_WAIT_V(8); PG8_WAIT_L(0); PG8_BAR; PG8_MMA(1, 0, At, B0); PG8_MMA(1, 1, At, B1); PG8_BAR; PG8_SCHED;
.LBB0_405:
	s_add_u32 s24, s8, 0xfffc0080
	s_addc_u32 s25, s9, -1
	s_cmp_eq_u32 s46, 12
	s_cselect_b32 s27, s7, s25
	s_cselect_b32 s26, s17, s24
	s_cselect_b32 s25, s19, s45
	s_cselect_b32 s24, s43, s44
	s_add_i32 s50, 0, 0x14000
	ds_read_b128 v[144:147], v164
	ds_read_b128 v[148:151], v164 offset:1024
	ds_read_b128 v[152:155], v164 offset:2048
	ds_read_b128 v[156:159], v164 offset:3072
	ds_read_b128 v[160:163], v164 offset:16384
	ds_read_b128 v[168:171], v164 offset:17408
	ds_read_b128 v[172:175], v164 offset:18432
	ds_read_b128 v[176:179], v164 offset:19456
	v_lshl_add_u64 v[198:199], s[8:9], 0, v[140:141]
	s_add_i32 m0, s37, 0xc000
	ds_read_b128 v[180:183], v166
	ds_read_b128 v[184:187], v166 offset:1024
	ds_read_b128 v[188:191], v166 offset:2048
	ds_read_b128 v[192:195], v166 offset:3072
	ds_read_b128 v[202:205], v166 offset:4096
	ds_read_b128 v[206:209], v166 offset:5120
	ds_read_b128 v[210:213], v166 offset:6144
	ds_read_b128 v[214:217], v166 offset:7168
	global_load_lds_dwordx4 v[198:199], off
	s_add_i32 m0, s37, 0xe000
	v_lshl_add_u64 v[198:199], s[8:9], 0, v[142:143]
	global_load_lds_dwordx4 v[198:199], off
	s_waitcnt vmcnt(8) lgkmcnt(0)
	s_barrier
	s_setprio 1
	v_mfma_f32_16x16x32_bf16 v[128:131], v[144:147], v[180:183], v[128:131]
	v_mfma_f32_16x16x32_bf16 v[120:123], v[152:155], v[180:183], v[120:123]
	v_mfma_f32_16x16x32_bf16 v[112:115], v[144:147], v[188:191], v[112:115]
	v_mfma_f32_16x16x32_bf16 v[104:107], v[152:155], v[188:191], v[104:107]
	v_mfma_f32_16x16x32_bf16 v[96:99], v[144:147], v[202:205], v[96:99]
	v_mfma_f32_16x16x32_bf16 v[88:91], v[152:155], v[202:205], v[88:91]
	v_mfma_f32_16x16x32_bf16 v[80:83], v[144:147], v[210:213], v[80:83]
	v_mfma_f32_16x16x32_bf16 v[72:75], v[152:155], v[210:213], v[72:75]
	v_mfma_f32_16x16x32_bf16 v[128:131], v[148:151], v[184:187], v[128:131]
	v_mfma_f32_16x16x32_bf16 v[120:123], v[156:159], v[184:187], v[120:123]
	v_mfma_f32_16x16x32_bf16 v[112:115], v[148:151], v[192:195], v[112:115]
	v_mfma_f32_16x16x32_bf16 v[104:107], v[156:159], v[192:195], v[104:107]
	v_mfma_f32_16x16x32_bf16 v[96:99], v[148:151], v[206:209], v[96:99]
	v_mfma_f32_16x16x32_bf16 v[88:91], v[156:159], v[206:209], v[88:91]
	v_mfma_f32_16x16x32_bf16 v[80:83], v[148:151], v[214:217], v[80:83]
	v_mfma_f32_16x16x32_bf16 v[72:75], v[156:159], v[214:217], v[72:75]
	s_setprio 0
	s_setprio 1
	v_mfma_f32_16x16x32_bf16 v[124:127], v[160:163], v[180:183], v[124:127]
	v_mfma_f32_16x16x32_bf16 v[116:119], v[172:175], v[180:183], v[116:119]
	v_mfma_f32_16x16x32_bf16 v[108:111], v[160:163], v[188:191], v[108:111]
	v_mfma_f32_16x16x32_bf16 v[100:103], v[172:175], v[188:191], v[100:103]
	v_mfma_f32_16x16x32_bf16 v[92:95], v[160:163], v[202:205], v[92:95]
	v_mfma_f32_16x16x32_bf16 v[84:87], v[172:175], v[202:205], v[84:87]
	v_mfma_f32_16x16x32_bf16 v[76:79], v[160:163], v[210:213], v[76:79]
	v_mfma_f32_16x16x32_bf16 v[68:71], v[172:175], v[210:213], v[68:71]
	v_mfma_f32_16x16x32_bf16 v[124:127], v[168:171], v[184:187], v[124:127]
	v_mfma_f32_16x16x32_bf16 v[116:119], v[176:179], v[184:187], v[116:119]
	v_mfma_f32_16x16x32_bf16 v[108:111], v[168:171], v[192:195], v[108:111]
	v_mfma_f32_16x16x32_bf16 v[100:103], v[176:179], v[192:195], v[100:103]
	v_mfma_f32_16x16x32_bf16 v[92:95], v[168:171], v[206:209], v[92:95]
	v_mfma_f32_16x16x32_bf16 v[84:87], v[176:179], v[206:209], v[84:87]
	v_mfma_f32_16x16x32_bf16 v[76:79], v[168:171], v[214:217], v[76:79]
	v_mfma_f32_16x16x32_bf16 v[68:71], v[176:179], v[214:217], v[68:71]
	s_setprio 0
	s_barrier
	v_lshl_add_u64 v[198:199], s[24:25], 0, v[134:135]
	s_add_i32 m0, s35, 0x10000
	ds_read_b128 v[180:183], v166 offset:16384
	ds_read_b128 v[184:187], v166 offset:17408
	ds_read_b128 v[188:191], v166 offset:18432
	ds_read_b128 v[192:195], v166 offset:19456
	ds_read_b128 v[202:205], v166 offset:20480
	ds_read_b128 v[206:209], v166 offset:21504
	ds_read_b128 v[210:213], v166 offset:22528
	ds_read_b128 v[214:217], v166 offset:23552
	global_load_lds_dwordx4 v[198:199], off
	s_add_i32 m0, s35, 0x12000
	s_add_u32 s48, s24, 0x40000
	v_lshl_add_u64 v[218:219], s[24:25], 0, v[0:1]
	s_addc_u32 s49, s25, 0
	global_load_lds_dwordx4 v[218:219], off
	v_lshl_add_u64 v[220:221], s[48:49], 0, v[134:135]
	s_add_i32 m0, s35, 0x14000
	v_lshl_add_u64 v[222:223], s[26:27], 0, v[132:133]
	global_load_lds_dwordx4 v[220:221], off
	s_add_i32 m0, s35, 0x16000
	v_lshl_add_u64 v[220:221], s[48:49], 0, v[0:1]
	global_load_lds_dwordx4 v[220:221], off
	s_mov_b32 m0, s37
	v_lshl_add_u64 v[220:221], s[26:27], 0, v[136:137]
	global_load_lds_dwordx4 v[220:221], off
	s_mov_b32 m0, s38
	s_add_i32 s47, 0, 0x18000
	global_load_lds_dwordx4 v[222:223], off
	s_waitcnt vmcnt(8) lgkmcnt(0)
	s_barrier
; #define PG8_STAGE(bufoff, gbase, voff) do { _Pragma("unroll") for (int _i = 0; _i < 2; ++_i) \
;         __builtin_amdgcn_global_load_lds((const unsigned*)((const char*)(gbase) + (voff)[_i]), (PG8_LAS unsigned*)(lds + (bufoff) + ldsw + _i * 8192), 16, 0, 0); } while (0)
; #define PG8_LDA(dst, b, h) do { _Pragma("unroll") for (int m = 0; m < 4; ++m) _Pragma("unroll") for (int k = 0; k < 2; ++k) dst[m][k] = *(const PG8_LAS bf16x8*)(lds + PG8_SA(b, h) + aoff + m * 2048 + k * 1024); } while (0)
; #define PG8_LDB(dst, b, h) do { _Pragma("unroll") for (int n = 0; n < 2; ++n) _Pragma("unroll") for (int k = 0; k < 2; ++k) dst[n][k] = *(const PG8_LAS bf16x8*)(lds + PG8_SB(b, h) + boff + n * 2048 + k * 1024); } while (0)
; #define PG8_MMA(ai, bj, At, Bt) do { __builtin_amdgcn_s_setprio(1); _Pragma("unroll") for (int m = 0; m < 4; ++m) _Pragma("unroll") for (int n = 0; n < 2; ++n) _Pragma("unroll") for (int k = 0; k < 2; ++k) \
;         acc[ai][bj][m][n] = __builtin_amdgcn_mfma_f32_16x16x32_bf16(Bt[n][k], At[m][k], acc[ai][bj][m][n], 0, 0, 0); __builtin_amdgcn_s_setprio(0); } while (0)
; #define PG8_WAIT_V(n) asm volatile("s_waitcnt vmcnt(" #n ")" ::: "memory")
; #define PG8_WAIT_L(n) asm volatile("s_waitcnt lgkmcnt(" #n ")" ::: "memory")
; #define PG8_BAR __builtin_amdgcn_s_barrier()
; #define PG8_SCHED __builtin_amdgcn_sched_barrier(0)
; template <class Epi, class Sched, bool ALIGN_EPI = false, bool SP2 = false>
; __device__ __forceinline__ void gemm_phase(PG8_LAS unsigned char* lds, const Gemm g, const Sched& S, const Epi& E) {
;     ...
;             PG8_WAIT_V(8); PG8_WAIT_L(0); PG8_BAR; PG8_MMA(1, 0, At, B0); PG8_MMA(1, 1, At, B1); PG8_BAR; PG8_SCHED;
;             PG8_LDB(B0, 1, 0); PG8_LDB(B1, 1, 1); PG8_SCHED; PG8_LDA(At, 1, 0); PG8_STAGE(PG8_SA(0, 1), a2 + hstep, voffA);
;             PG8_WAIT_V(8); PG8_WAIT_L(0); PG8_BAR; PG8_MMA(0, 0, At, B0); PG8_MMA(0, 1, At, B1); PG8_BAR; PG8_SCHED;
	s_setprio 1
	v_mfma_f32_16x16x32_bf16 v[64:67], v[144:147], v[180:183], v[64:67]
	v_mfma_f32_16x16x32_bf16 v[56:59], v[152:155], v[180:183], v[56:59]
	v_mfma_f32_16x16x32_bf16 v[48:51], v[144:147], v[188:191], v[48:51]
	v_mfma_f32_16x16x32_bf16 v[40:43], v[152:155], v[188:191], v[40:43]
	v_mfma_f32_16x16x32_bf16 v[32:35], v[144:147], v[202:205], v[32:35]
	v_mfma_f32_16x16x32_bf16 v[24:27], v[152:155], v[202:205], v[24:27]
	v_mfma_f32_16x16x32_bf16 v[16:19], v[144:147], v[210:213], v[16:19]
	v_mfma_f32_16x16x32_bf16 v[8:11], v[152:155], v[210:213], v[8:11]
	v_mfma_f32_16x16x32_bf16 v[64:67], v[148:151], v[184:187], v[64:67]
	v_mfma_f32_16x16x32_bf16 v[56:59], v[156:159], v[184:187], v[56:59]
	v_mfma_f32_16x16x32_bf16 v[48:51], v[148:151], v[192:195], v[48:51]
	v_mfma_f32_16x16x32_bf16 v[40:43], v[156:159], v[192:195], v[40:43]
	v_mfma_f32_16x16x32_bf16 v[32:35], v[148:151], v[206:209], v[32:35]
	v_mfma_f32_16x16x32_bf16 v[24:27], v[156:159], v[206:209], v[24:27]
	v_mfma_f32_16x16x32_bf16 v[16:19], v[148:151], v[214:217], v[16:19]
	v_mfma_f32_16x16x32_bf16 v[8:11], v[156:159], v[214:217], v[8:11]
	s_setprio 0
	s_setprio 1
	v_mfma_f32_16x16x32_bf16 v[60:63], v[160:163], v[180:183], v[60:63]
	v_mfma_f32_16x16x32_bf16 v[52:55], v[172:175], v[180:183], v[52:55]
	v_mfma_f32_16x16x32_bf16 v[44:47], v[160:163], v[188:191], v[44:47]
	v_mfma_f32_16x16x32_bf16 v[36:39], v[172:175], v[188:191], v[36:39]
	v_mfma_f32_16x16x32_bf16 v[28:31], v[160:163], v[202:205], v[28:31]
	v_mfma_f32_16x16x32_bf16 v[20:23], v[172:175], v[202:205], v[20:23]
	v_mfma_f32_16x16x32_bf16 v[12:15], v[160:163], v[210:213], v[12:15]
	v_mfma_f32_16x16x32_bf16 v[4:7], v[172:175], v[210:213], v[4:7]
	v_mfma_f32_16x16x32_bf16 v[60:63], v[168:171], v[184:187], v[60:63]
	v_mfma_f32_16x16x32_bf16 v[52:55], v[176:179], v[184:187], v[52:55]
	v_mfma_f32_16x16x32_bf16 v[44:47], v[168:171], v[192:195], v[44:47]
	v_mfma_f32_16x16x32_bf16 v[36:39], v[176:179], v[192:195], v[36:39]
	v_mfma_f32_16x16x32_bf16 v[28:31], v[168:171], v[206:209], v[28:31]
	v_mfma_f32_16x16x32_bf16 v[20:23], v[176:179], v[206:209], v[20:23]
	v_mfma_f32_16x16x32_bf16 v[12:15], v[168:171], v[214:217], v[12:15]
	v_mfma_f32_16x16x32_bf16 v[4:7], v[176:179], v[214:217], v[4:7]
	s_setprio 0
	s_barrier
	ds_read_b128 v[144:147], v164 offset:32768
	ds_read_b128 v[148:151], v164 offset:33792
	ds_read_b128 v[152:155], v164 offset:34816
	ds_read_b128 v[156:159], v164 offset:35840
	ds_read_b128 v[160:163], v164 offset:49152
	ds_read_b128 v[168:171], v164 offset:50176
	ds_read_b128 v[172:175], v164 offset:51200
	ds_read_b128 v[176:179], v164 offset:52224
	s_add_u32 s26, s26, 0x40000
	s_addc_u32 s27, s27, 0
	s_mov_b32 m0, s39
	v_lshl_add_u64 v[224:225], s[26:27], 0, v[136:137]
	ds_read_b128 v[180:183], v166 offset:32768
	ds_read_b128 v[184:187], v166 offset:33792
	ds_read_b128 v[188:191], v166 offset:34816
	ds_read_b128 v[192:195], v166 offset:35840
	ds_read_b128 v[202:205], v166 offset:36864
	ds_read_b128 v[206:209], v166 offset:37888
	ds_read_b128 v[210:213], v166 offset:38912
	ds_read_b128 v[214:217], v166 offset:39936
	global_load_lds_dwordx4 v[224:225], off
	s_mov_b32 m0, s40
	v_lshl_add_u64 v[224:225], s[26:27], 0, v[132:133]
	global_load_lds_dwordx4 v[224:225], off
	s_waitcnt vmcnt(8) lgkmcnt(0)
	s_barrier
	s_setprio 1
	v_mfma_f32_16x16x32_bf16 v[128:131], v[144:147], v[180:183], v[128:131]
	v_mfma_f32_16x16x32_bf16 v[120:123], v[152:155], v[180:183], v[120:123]
	v_mfma_f32_16x16x32_bf16 v[112:115], v[144:147], v[188:191], v[112:115]
	v_mfma_f32_16x16x32_bf16 v[104:107], v[152:155], v[188:191], v[104:107]
	v_mfma_f32_16x16x32_bf16 v[96:99], v[144:147], v[202:205], v[96:99]
	v_mfma_f32_16x16x32_bf16 v[88:91], v[152:155], v[202:205], v[88:91]
	v_mfma_f32_16x16x32_bf16 v[80:83], v[144:147], v[210:213], v[80:83]
	v_mfma_f32_16x16x32_bf16 v[72:75], v[152:155], v[210:213], v[72:75]
	v_mfma_f32_16x16x32_bf16 v[128:131], v[148:151], v[184:187], v[128:131]
	v_mfma_f32_16x16x32_bf16 v[120:123], v[156:159], v[184:187], v[120:123]
	v_mfma_f32_16x16x32_bf16 v[112:115], v[148:151], v[192:195], v[112:115]
	v_mfma_f32_16x16x32_bf16 v[104:107], v[156:159], v[192:195], v[104:107]
	v_mfma_f32_16x16x32_bf16 v[96:99], v[148:151], v[206:209], v[96:99]
	v_mfma_f32_16x16x32_bf16 v[88:91], v[156:159], v[206:209], v[88:91]
	v_mfma_f32_16x16x32_bf16 v[80:83], v[148:151], v[214:217], v[80:83]
	v_mfma_f32_16x16x32_bf16 v[72:75], v[156:159], v[214:217], v[72:75]
	s_setprio 0
	s_setprio 1
	v_mfma_f32_16x16x32_bf16 v[124:127], v[160:163], v[180:183], v[124:127]
	v_mfma_f32_16x16x32_bf16 v[116:119], v[172:175], v[180:183], v[116:119]
	v_mfma_f32_16x16x32_bf16 v[108:111], v[160:163], v[188:191], v[108:111]
	v_mfma_f32_16x16x32_bf16 v[100:103], v[172:175], v[188:191], v[100:103]
	v_mfma_f32_16x16x32_bf16 v[92:95], v[160:163], v[202:205], v[92:95]
	v_mfma_f32_16x16x32_bf16 v[84:87], v[172:175], v[202:205], v[84:87]
	v_mfma_f32_16x16x32_bf16 v[76:79], v[160:163], v[210:213], v[76:79]
	v_mfma_f32_16x16x32_bf16 v[68:71], v[172:175], v[210:213], v[68:71]
	v_mfma_f32_16x16x32_bf16 v[124:127], v[168:171], v[184:187], v[124:127]
	v_mfma_f32_16x16x32_bf16 v[116:119], v[176:179], v[184:187], v[116:119]
	v_mfma_f32_16x16x32_bf16 v[108:111], v[168:171], v[192:195], v[108:111]
	v_mfma_f32_16x16x32_bf16 v[100:103], v[176:179], v[192:195], v[100:103]
	v_mfma_f32_16x16x32_bf16 v[92:95], v[168:171], v[206:209], v[92:95]
	v_mfma_f32_16x16x32_bf16 v[84:87], v[176:179], v[206:209], v[84:87]
	v_mfma_f32_16x16x32_bf16 v[76:79], v[168:171], v[214:217], v[76:79]
	v_mfma_f32_16x16x32_bf16 v[68:71], v[176:179], v[214:217], v[68:71]
	s_setprio 0
	s_barrier
; #define PG8_STAGE(bufoff, gbase, voff) do { _Pragma("unroll") for (int _i = 0; _i < 2; ++_i) \
;         __builtin_amdgcn_global_load_lds((const unsigned*)((const char*)(gbase) + (voff)[_i]), (PG8_LAS unsigned*)(lds + (bufoff) + ldsw + _i * 8192), 16, 0, 0); } while (0)
; #define PG8_LDA(dst, b, h) do { _Pragma("unroll") for (int m = 0; m < 4; ++m) _Pragma("unroll") for (int k = 0; k < 2; ++k) dst[m][k] = *(const PG8_LAS bf16x8*)(lds + PG8_SA(b, h) + aoff + m * 2048 + k * 1024); } while (0)
; #define PG8_MMA(ai, bj, At, Bt) do { __builtin_amdgcn_s_setprio(1); _Pragma("unroll") for (int m = 0; m < 4; ++m) _Pragma("unroll") for (int n = 0; n < 2; ++n) _Pragma("unroll") for (int k = 0; k < 2; ++k) \
;         acc[ai][bj][m][n] = __builtin_amdgcn_mfma_f32_16x16x32_bf16(Bt[n][k], At[m][k], acc[ai][bj][m][n], 0, 0, 0); __builtin_amdgcn_s_setprio(0); } while (0)
; #define PG8_WAIT_V(n) asm volatile("s_waitcnt vmcnt(" #n ")" ::: "memory")
; #define PG8_WAIT_L(n) asm volatile("s_waitcnt lgkmcnt(" #n ")" ::: "memory")
; #define PG8_BAR __builtin_amdgcn_s_barrier()
; #define PG8_SCHED __builtin_amdgcn_sched_barrier(0)
; template <class Epi, class Sched, bool ALIGN_EPI = false, bool SP2 = false>
; __device__ __forceinline__ void gemm_phase(PG8_LAS unsigned char* lds, const Gemm g, const Sched& S, const Epi& E) {
;     ...
;         for (int t = 0; t < nt; t += 2) {
;             const bool last = (t == nt - 2);
;             const char* a1 = cA + (size_t)(t + 1) * kstep;
;             const char* a2 = last ? nA : cA + (size_t)(t + 2) * kstep; const char* b2 = last ? nB : cB + (size_t)(t + 2) * kstep;
;             const char* a3 = a2 + kstep; const char* b3 = b2 + kstep;
;             if (last && has_next) S.a_ready(nxt);
;     ...
;             PG8_LDA(At, 1, 1); PG8_STAGE(PG8_SB(1, 0), b3, voffB); PG8_STAGE(PG8_SB(1, 1), b3 + hstep, voffB); PG8_STAGE(PG8_SA(1, 0), a3, voffA);
;             PG8_WAIT_V(8); PG8_WAIT_L(0); PG8_BAR; PG8_MMA(1, 0, At, B0); PG8_MMA(1, 1, At, B1); PG8_BAR; PG8_SCHED;
	s_add_i32 m0, s35, 0x17f80
	ds_read_b128 v[180:183], v166 offset:49152
	ds_read_b128 v[184:187], v166 offset:50176
	ds_read_b128 v[188:191], v166 offset:51200
	ds_read_b128 v[192:195], v166 offset:52224
	ds_read_b128 v[202:205], v166 offset:53248
	ds_read_b128 v[206:209], v166 offset:54272
	ds_read_b128 v[210:213], v166 offset:55296
	ds_read_b128 v[214:217], v166 offset:56320
	global_load_lds_dwordx4 v[198:199], off offset:128
	s_add_i32 m0, s35, 0x19f80
	s_add_u32 s24, s24, 0x40080
	s_addc_u32 s25, s25, 0
	global_load_lds_dwordx4 v[218:219], off offset:128
	s_add_i32 m0, s35, 0x1c000
	v_lshl_add_u64 v[198:199], s[24:25], 0, v[134:135]
	global_load_lds_dwordx4 v[198:199], off
	s_add_i32 m0, s35, 0x1e000
	v_lshl_add_u64 v[198:199], s[24:25], 0, v[0:1]
	global_load_lds_dwordx4 v[198:199], off
	s_add_i32 m0, s41, 0xffffff80
	s_add_u32 s8, s8, 0x100
	s_addc_u32 s9, s9, 0
	global_load_lds_dwordx4 v[220:221], off offset:128
	s_add_i32 m0, s42, 0xffffff80
	s_add_u32 s44, s44, 0x100
	s_addc_u32 s45, s45, 0
	global_load_lds_dwordx4 v[222:223], off offset:128
	s_waitcnt vmcnt(8) lgkmcnt(0)
	s_barrier
	s_setprio 1
	v_mfma_f32_16x16x32_bf16 v[64:67], v[144:147], v[180:183], v[64:67]
	v_mfma_f32_16x16x32_bf16 v[56:59], v[152:155], v[180:183], v[56:59]
	v_mfma_f32_16x16x32_bf16 v[48:51], v[144:147], v[188:191], v[48:51]
	v_mfma_f32_16x16x32_bf16 v[40:43], v[152:155], v[188:191], v[40:43]
	v_mfma_f32_16x16x32_bf16 v[32:35], v[144:147], v[202:205], v[32:35]
	v_mfma_f32_16x16x32_bf16 v[24:27], v[152:155], v[202:205], v[24:27]
	v_mfma_f32_16x16x32_bf16 v[16:19], v[144:147], v[210:213], v[16:19]
	v_mfma_f32_16x16x32_bf16 v[8:11], v[152:155], v[210:213], v[8:11]
	v_mfma_f32_16x16x32_bf16 v[64:67], v[148:151], v[184:187], v[64:67]
	v_mfma_f32_16x16x32_bf16 v[56:59], v[156:159], v[184:187], v[56:59]
	v_mfma_f32_16x16x32_bf16 v[48:51], v[148:151], v[192:195], v[48:51]
	v_mfma_f32_16x16x32_bf16 v[40:43], v[156:159], v[192:195], v[40:43]
	v_mfma_f32_16x16x32_bf16 v[32:35], v[148:151], v[206:209], v[32:35]
	v_mfma_f32_16x16x32_bf16 v[24:27], v[156:159], v[206:209], v[24:27]
	v_mfma_f32_16x16x32_bf16 v[16:19], v[148:151], v[214:217], v[16:19]
	v_mfma_f32_16x16x32_bf16 v[8:11], v[156:159], v[214:217], v[8:11]
	s_setprio 0
	s_setprio 1
	v_mfma_f32_16x16x32_bf16 v[60:63], v[160:163], v[180:183], v[60:63]
	v_mfma_f32_16x16x32_bf16 v[52:55], v[172:175], v[180:183], v[52:55]
	v_mfma_f32_16x16x32_bf16 v[44:47], v[160:163], v[188:191], v[44:47]
	v_mfma_f32_16x16x32_bf16 v[36:39], v[172:175], v[188:191], v[36:39]
	v_mfma_f32_16x16x32_bf16 v[28:31], v[160:163], v[202:205], v[28:31]
	v_mfma_f32_16x16x32_bf16 v[20:23], v[172:175], v[202:205], v[20:23]
	v_mfma_f32_16x16x32_bf16 v[12:15], v[160:163], v[210:213], v[12:15]
	v_mfma_f32_16x16x32_bf16 v[4:7], v[172:175], v[210:213], v[4:7]
	v_mfma_f32_16x16x32_bf16 v[60:63], v[168:171], v[184:187], v[60:63]
	v_mfma_f32_16x16x32_bf16 v[52:55], v[176:179], v[184:187], v[52:55]
	v_mfma_f32_16x16x32_bf16 v[44:47], v[168:171], v[192:195], v[44:47]
	v_mfma_f32_16x16x32_bf16 v[36:39], v[176:179], v[192:195], v[36:39]
	v_mfma_f32_16x16x32_bf16 v[28:31], v[168:171], v[206:209], v[28:31]
	v_mfma_f32_16x16x32_bf16 v[20:23], v[176:179], v[206:209], v[20:23]
	v_mfma_f32_16x16x32_bf16 v[12:15], v[168:171], v[214:217], v[12:15]
	v_mfma_f32_16x16x32_bf16 v[4:7], v[176:179], v[214:217], v[4:7]
	s_setprio 0
	s_barrier
	s_add_i32 s46, s46, 2
	s_cmp_gt_u32 s46, 13
	s_cbranch_scc0 .LBB0_405
	s_and_b64 vcc, exec, s[14:15]
	s_cbranch_vccz .LBB0_408
	s_barrier

; #define PG8_STAGE(bufoff, gbase, voff) do { _Pragma("unroll") for (int _i = 0; _i < 2; ++_i) \
;         __builtin_amdgcn_global_load_lds((const unsigned*)((const char*)(gbase) + (voff)[_i]), (PG8_LAS unsigned*)(lds + (bufoff) + ldsw + _i * 8192), 16, 0, 0); } while (0)
; #define PG8_LDA(dst, b, h) do { _Pragma("unroll") for (int m = 0; m < 4; ++m) _Pragma("unroll") for (int k = 0; k < 2; ++k) dst[m][k] = *(const PG8_LAS bf16x8*)(lds + PG8_SA(b, h) + aoff + m * 2048 + k * 1024); } while (0)
; #define PG8_LDB(dst, b, h) do { _Pragma("unroll") for (int n = 0; n < 2; ++n) _Pragma("unroll") for (int k = 0; k < 2; ++k) dst[n][k] = *(const PG8_LAS bf16x8*)(lds + PG8_SB(b, h) + boff + n * 2048 + k * 1024); } while (0)
; #define PG8_MMA(ai, bj, At, Bt) do { __builtin_amdgcn_s_setprio(1); _Pragma("unroll") for (int m = 0; m < 4; ++m) _Pragma("unroll") for (int n = 0; n < 2; ++n) _Pragma("unroll") for (int k = 0; k < 2; ++k) \
;         acc[ai][bj][m][n] = __builtin_amdgcn_mfma_f32_16x16x32_bf16(Bt[n][k], At[m][k], acc[ai][bj][m][n], 0, 0, 0); __builtin_amdgcn_s_setprio(0); } while (0)
; #define PG8_WAIT_V(n) asm volatile("s_waitcnt vmcnt(" #n ")" ::: "memory")
; #define PG8_WAIT_L(n) asm volatile("s_waitcnt lgkmcnt(" #n ")" ::: "memory")
; #define PG8_BAR __builtin_amdgcn_s_barrier()
; template <class Epi, class Sched, bool ALIGN_EPI = false, bool SP2 = false>
; __device__ __forceinline__ void gemm_phase(PG8_LAS unsigned char* lds, const Gemm g, const Sched& S, const Epi& E) {
;     ...
;             const char* a1 = cA + (size_t)(t + 1) * kstep;
;             const char* a2 = last ? nA : cA + (size_t)(t + 2) * kstep; const char* b2 = last ? nB : cB + (size_t)(t + 2) * kstep;
;             const char* a3 = a2 + kstep; const char* b3 = b2 + kstep;
;             if (last && has_next) S.a_ready(nxt);
;             if constexpr (SP2) {
;             PG8_LDB(B0, 0, 0); PG8_LDB(B1, 0, 1); PG8_SCHED; PG8_LDA(At, 0, 0); PG8_STAGE(PG8_SA(1, 1), a1 + hstep, voffA);
;             PG8_WAIT_V(8); PG8_WAIT_L(0); PG8_BAR; PG8_MMA(0, 0, At, B0); PG8_MMA(0, 1, At, B1); PG8_BAR; PG8_SCHED;
;             PG8_LDA(At, 0, 1); PG8_STAGE(PG8_SB(0, 0), b2, voffB); PG8_STAGE(PG8_SB(0, 1), b2 + hstep, voffB); PG8_STAGE(PG8_SA(0, 0), a2, voffA);
;             PG8_WAIT_V(8); PG8_WAIT_L(0); PG8_BAR; PG8_MMA(1, 0, At, B0); PG8_MMA(1, 1, At, B1); PG8_BAR; PG8_SCHED;
.LBB0_480:
	s_add_u32 s8, s26, 0x100
	s_addc_u32 s9, s27, 0
	s_cmp_eq_u32 s53, 40
	s_cselect_b32 s31, s23, s9
	s_cselect_b32 s30, s22, s8
	s_cselect_b32 s29, s25, s45
	s_cselect_b32 s28, s24, s44
	ds_read_b128 v[68:71], v234
	ds_read_b128 v[80:83], v234 offset:1024
	ds_read_b128 v[92:95], v234 offset:2048
	ds_read_b128 v[100:103], v234 offset:3072
	ds_read_b128 v[112:115], v234 offset:16384
	ds_read_b128 v[120:123], v234 offset:17408
	ds_read_b128 v[132:135], v234 offset:18432
	ds_read_b128 v[144:147], v234 offset:19456
	v_lshl_add_u64 v[198:199], s[26:27], 0, v[204:205]
	s_add_i32 m0, s40, 0xc000
	ds_read_b128 v[156:159], v236
	ds_read_b128 v[168:171], v236 offset:1024
	ds_read_b128 v[172:175], v236 offset:2048
	ds_read_b128 v[176:179], v236 offset:3072
	ds_read_b128 v[180:183], v236 offset:4096
	ds_read_b128 v[184:187], v236 offset:5120
	ds_read_b128 v[188:191], v236 offset:6144
	ds_read_b128 v[208:211], v236 offset:7168
	global_load_lds_dwordx4 v[198:199], off
	s_add_i32 m0, s40, 0xe000
	v_lshl_add_u64 v[198:199], s[26:27], 0, v[206:207]
	global_load_lds_dwordx4 v[198:199], off
	s_waitcnt vmcnt(8) lgkmcnt(0)
	s_barrier
	s_setprio 1
	v_mfma_f32_16x16x32_bf16 v[164:167], v[68:71], v[156:159], v[164:167]
	v_mfma_f32_16x16x32_bf16 v[160:163], v[92:95], v[156:159], v[160:163]
	v_mfma_f32_16x16x32_bf16 v[140:143], v[68:71], v[172:175], v[140:143]
	v_mfma_f32_16x16x32_bf16 v[136:139], v[92:95], v[172:175], v[136:139]
	v_mfma_f32_16x16x32_bf16 v[116:119], v[68:71], v[180:183], v[116:119]
	v_mfma_f32_16x16x32_bf16 v[108:111], v[92:95], v[180:183], v[108:111]
	v_mfma_f32_16x16x32_bf16 v[88:91], v[68:71], v[188:191], v[88:91]
	v_mfma_f32_16x16x32_bf16 v[84:87], v[92:95], v[188:191], v[84:87]
	v_mfma_f32_16x16x32_bf16 v[164:167], v[80:83], v[168:171], v[164:167]
	v_mfma_f32_16x16x32_bf16 v[160:163], v[100:103], v[168:171], v[160:163]
	v_mfma_f32_16x16x32_bf16 v[140:143], v[80:83], v[176:179], v[140:143]
	v_mfma_f32_16x16x32_bf16 v[136:139], v[100:103], v[176:179], v[136:139]
	v_mfma_f32_16x16x32_bf16 v[116:119], v[80:83], v[184:187], v[116:119]
	v_mfma_f32_16x16x32_bf16 v[108:111], v[100:103], v[184:187], v[108:111]
	v_mfma_f32_16x16x32_bf16 v[88:91], v[80:83], v[208:211], v[88:91]
	v_mfma_f32_16x16x32_bf16 v[84:87], v[100:103], v[208:211], v[84:87]
	s_setprio 0
	s_setprio 1
	v_mfma_f32_16x16x32_bf16 v[152:155], v[112:115], v[156:159], v[152:155]
	v_mfma_f32_16x16x32_bf16 v[148:151], v[132:135], v[156:159], v[148:151]
	v_mfma_f32_16x16x32_bf16 v[128:131], v[112:115], v[172:175], v[128:131]
	v_mfma_f32_16x16x32_bf16 v[124:127], v[132:135], v[172:175], v[124:127]
	v_mfma_f32_16x16x32_bf16 v[104:107], v[112:115], v[180:183], v[104:107]
	v_mfma_f32_16x16x32_bf16 v[96:99], v[132:135], v[180:183], v[96:99]
	v_mfma_f32_16x16x32_bf16 v[76:79], v[112:115], v[188:191], v[76:79]
	v_mfma_f32_16x16x32_bf16 v[72:75], v[132:135], v[188:191], v[72:75]
	v_mfma_f32_16x16x32_bf16 v[152:155], v[120:123], v[168:171], v[152:155]
	v_mfma_f32_16x16x32_bf16 v[148:151], v[144:147], v[168:171], v[148:151]
	v_mfma_f32_16x16x32_bf16 v[128:131], v[120:123], v[176:179], v[128:131]
	v_mfma_f32_16x16x32_bf16 v[124:127], v[144:147], v[176:179], v[124:127]
	v_mfma_f32_16x16x32_bf16 v[104:107], v[120:123], v[184:187], v[104:107]
	v_mfma_f32_16x16x32_bf16 v[96:99], v[144:147], v[184:187], v[96:99]
	v_mfma_f32_16x16x32_bf16 v[76:79], v[120:123], v[208:211], v[76:79]
	v_mfma_f32_16x16x32_bf16 v[72:75], v[144:147], v[208:211], v[72:75]
	s_setprio 0
	s_barrier
	v_lshl_add_u64 v[198:199], s[28:29], 0, v[192:193]
	s_add_i32 m0, s39, 0x10000
	ds_read_b128 v[156:159], v236 offset:16384
	ds_read_b128 v[168:171], v236 offset:17408
	ds_read_b128 v[172:175], v236 offset:18432
	ds_read_b128 v[176:179], v236 offset:19456
	ds_read_b128 v[180:183], v236 offset:20480
	ds_read_b128 v[184:187], v236 offset:21504
	ds_read_b128 v[188:191], v236 offset:22528
	ds_read_b128 v[208:211], v236 offset:23552
	global_load_lds_dwordx4 v[198:199], off
	s_add_i32 m0, s39, 0x12000
	s_add_u32 s26, s28, 0xb0000
	v_lshl_add_u64 v[212:213], s[28:29], 0, v[202:203]
	s_addc_u32 s27, s29, 0
	global_load_lds_dwordx4 v[212:213], off
	v_lshl_add_u64 v[214:215], s[26:27], 0, v[192:193]
	s_add_i32 m0, s39, 0x14000
	v_lshl_add_u64 v[216:217], s[30:31], 0, v[194:195]
	global_load_lds_dwordx4 v[214:215], off
	s_add_i32 m0, s39, 0x16000
	v_lshl_add_u64 v[214:215], s[26:27], 0, v[202:203]
	global_load_lds_dwordx4 v[214:215], off
	s_mov_b32 m0, s40
	v_lshl_add_u64 v[214:215], s[30:31], 0, v[0:1]
	global_load_lds_dwordx4 v[214:215], off
	s_mov_b32 m0, s41
	s_add_i32 s54, 0, 0x18000
	global_load_lds_dwordx4 v[216:217], off
	s_waitcnt vmcnt(8) lgkmcnt(0)
	s_barrier
; #define PG8_STAGE(bufoff, gbase, voff) do { _Pragma("unroll") for (int _i = 0; _i < 2; ++_i) \
;         __builtin_amdgcn_global_load_lds((const unsigned*)((const char*)(gbase) + (voff)[_i]), (PG8_LAS unsigned*)(lds + (bufoff) + ldsw + _i * 8192), 16, 0, 0); } while (0)
; #define PG8_LDA(dst, b, h) do { _Pragma("unroll") for (int m = 0; m < 4; ++m) _Pragma("unroll") for (int k = 0; k < 2; ++k) dst[m][k] = *(const PG8_LAS bf16x8*)(lds + PG8_SA(b, h) + aoff + m * 2048 + k * 1024); } while (0)
; #define PG8_LDB(dst, b, h) do { _Pragma("unroll") for (int n = 0; n < 2; ++n) _Pragma("unroll") for (int k = 0; k < 2; ++k) dst[n][k] = *(const PG8_LAS bf16x8*)(lds + PG8_SB(b, h) + boff + n * 2048 + k * 1024); } while (0)
; #define PG8_MMA(ai, bj, At, Bt) do { __builtin_amdgcn_s_setprio(1); _Pragma("unroll") for (int m = 0; m < 4; ++m) _Pragma("unroll") for (int n = 0; n < 2; ++n) _Pragma("unroll") for (int k = 0; k < 2; ++k) \
;         acc[ai][bj][m][n] = __builtin_amdgcn_mfma_f32_16x16x32_bf16(Bt[n][k], At[m][k], acc[ai][bj][m][n], 0, 0, 0); __builtin_amdgcn_s_setprio(0); } while (0)
; #define PG8_WAIT_V(n) asm volatile("s_waitcnt vmcnt(" #n ")" ::: "memory")
; #define PG8_WAIT_L(n) asm volatile("s_waitcnt lgkmcnt(" #n ")" ::: "memory")
; #define PG8_BAR __builtin_amdgcn_s_barrier()
; #define PG8_SCHED __builtin_amdgcn_sched_barrier(0)
; template <class Epi, class Sched, bool ALIGN_EPI = false, bool SP2 = false>
; __device__ __forceinline__ void gemm_phase(PG8_LAS unsigned char* lds, const Gemm g, const Sched& S, const Epi& E) {
;     ...
;             PG8_WAIT_V(8); PG8_WAIT_L(0); PG8_BAR; PG8_MMA(1, 0, At, B0); PG8_MMA(1, 1, At, B1); PG8_BAR; PG8_SCHED;
;             PG8_LDB(B0, 1, 0); PG8_LDB(B1, 1, 1); PG8_SCHED; PG8_LDA(At, 1, 0); PG8_STAGE(PG8_SA(0, 1), a2 + hstep, voffA);
;             PG8_WAIT_V(8); PG8_WAIT_L(0); PG8_BAR; PG8_MMA(0, 0, At, B0); PG8_MMA(0, 1, At, B1); PG8_BAR; PG8_SCHED;
	s_setprio 1
	v_mfma_f32_16x16x32_bf16 v[64:67], v[68:71], v[156:159], v[64:67]
	v_mfma_f32_16x16x32_bf16 v[60:63], v[92:95], v[156:159], v[60:63]
	v_mfma_f32_16x16x32_bf16 v[48:51], v[68:71], v[172:175], v[48:51]
	v_mfma_f32_16x16x32_bf16 v[44:47], v[92:95], v[172:175], v[44:47]
	v_mfma_f32_16x16x32_bf16 v[32:35], v[68:71], v[180:183], v[32:35]
	v_mfma_f32_16x16x32_bf16 v[28:31], v[92:95], v[180:183], v[28:31]
	v_mfma_f32_16x16x32_bf16 v[16:19], v[68:71], v[188:191], v[16:19]
	v_mfma_f32_16x16x32_bf16 v[12:15], v[92:95], v[188:191], v[12:15]
	v_mfma_f32_16x16x32_bf16 v[64:67], v[80:83], v[168:171], v[64:67]
	v_mfma_f32_16x16x32_bf16 v[60:63], v[100:103], v[168:171], v[60:63]
	v_mfma_f32_16x16x32_bf16 v[48:51], v[80:83], v[176:179], v[48:51]
	v_mfma_f32_16x16x32_bf16 v[44:47], v[100:103], v[176:179], v[44:47]
	v_mfma_f32_16x16x32_bf16 v[32:35], v[80:83], v[184:187], v[32:35]
	v_mfma_f32_16x16x32_bf16 v[28:31], v[100:103], v[184:187], v[28:31]
	v_mfma_f32_16x16x32_bf16 v[16:19], v[80:83], v[208:211], v[16:19]
	v_mfma_f32_16x16x32_bf16 v[12:15], v[100:103], v[208:211], v[12:15]
	s_setprio 0
	s_setprio 1
	v_mfma_f32_16x16x32_bf16 v[56:59], v[112:115], v[156:159], v[56:59]
	v_mfma_f32_16x16x32_bf16 v[52:55], v[132:135], v[156:159], v[52:55]
	v_mfma_f32_16x16x32_bf16 v[40:43], v[112:115], v[172:175], v[40:43]
	v_mfma_f32_16x16x32_bf16 v[36:39], v[132:135], v[172:175], v[36:39]
	v_mfma_f32_16x16x32_bf16 v[24:27], v[112:115], v[180:183], v[24:27]
	v_mfma_f32_16x16x32_bf16 v[20:23], v[132:135], v[180:183], v[20:23]
	v_mfma_f32_16x16x32_bf16 v[8:11], v[112:115], v[188:191], v[8:11]
	v_mfma_f32_16x16x32_bf16 v[4:7], v[132:135], v[188:191], v[4:7]
	v_mfma_f32_16x16x32_bf16 v[56:59], v[120:123], v[168:171], v[56:59]
	v_mfma_f32_16x16x32_bf16 v[52:55], v[144:147], v[168:171], v[52:55]
	v_mfma_f32_16x16x32_bf16 v[40:43], v[120:123], v[176:179], v[40:43]
	v_mfma_f32_16x16x32_bf16 v[36:39], v[144:147], v[176:179], v[36:39]
	v_mfma_f32_16x16x32_bf16 v[24:27], v[120:123], v[184:187], v[24:27]
	v_mfma_f32_16x16x32_bf16 v[20:23], v[144:147], v[184:187], v[20:23]
	v_mfma_f32_16x16x32_bf16 v[8:11], v[120:123], v[208:211], v[8:11]
	v_mfma_f32_16x16x32_bf16 v[4:7], v[144:147], v[208:211], v[4:7]
	s_setprio 0
	s_barrier
	ds_read_b128 v[68:71], v234 offset:32768
	ds_read_b128 v[80:83], v234 offset:33792
	ds_read_b128 v[92:95], v234 offset:34816
	ds_read_b128 v[100:103], v234 offset:35840
	ds_read_b128 v[112:115], v234 offset:49152
	ds_read_b128 v[120:123], v234 offset:50176
	ds_read_b128 v[132:135], v234 offset:51200
	ds_read_b128 v[144:147], v234 offset:52224
	s_add_u32 s26, s30, 0xb0000
	s_addc_u32 s27, s31, 0
	s_mov_b32 m0, s42
	v_lshl_add_u64 v[218:219], s[26:27], 0, v[0:1]
	ds_read_b128 v[156:159], v236 offset:32768
	ds_read_b128 v[168:171], v236 offset:33792
	ds_read_b128 v[172:175], v236 offset:34816
	ds_read_b128 v[176:179], v236 offset:35840
	ds_read_b128 v[180:183], v236 offset:36864
	ds_read_b128 v[184:187], v236 offset:37888
	ds_read_b128 v[188:191], v236 offset:38912
	ds_read_b128 v[208:211], v236 offset:39936
	global_load_lds_dwordx4 v[218:219], off
	s_mov_b32 m0, s43
	v_lshl_add_u64 v[218:219], s[26:27], 0, v[194:195]
	global_load_lds_dwordx4 v[218:219], off
	s_waitcnt vmcnt(8) lgkmcnt(0)
	s_barrier
	s_setprio 1
	v_mfma_f32_16x16x32_bf16 v[164:167], v[68:71], v[156:159], v[164:167]
	v_mfma_f32_16x16x32_bf16 v[160:163], v[92:95], v[156:159], v[160:163]
	v_mfma_f32_16x16x32_bf16 v[140:143], v[68:71], v[172:175], v[140:143]
	v_mfma_f32_16x16x32_bf16 v[136:139], v[92:95], v[172:175], v[136:139]
	v_mfma_f32_16x16x32_bf16 v[116:119], v[68:71], v[180:183], v[116:119]
	v_mfma_f32_16x16x32_bf16 v[108:111], v[92:95], v[180:183], v[108:111]
	v_mfma_f32_16x16x32_bf16 v[88:91], v[68:71], v[188:191], v[88:91]
	v_mfma_f32_16x16x32_bf16 v[84:87], v[92:95], v[188:191], v[84:87]
	v_mfma_f32_16x16x32_bf16 v[164:167], v[80:83], v[168:171], v[164:167]
	v_mfma_f32_16x16x32_bf16 v[160:163], v[100:103], v[168:171], v[160:163]
	v_mfma_f32_16x16x32_bf16 v[140:143], v[80:83], v[176:179], v[140:143]
	v_mfma_f32_16x16x32_bf16 v[136:139], v[100:103], v[176:179], v[136:139]
	v_mfma_f32_16x16x32_bf16 v[116:119], v[80:83], v[184:187], v[116:119]
	v_mfma_f32_16x16x32_bf16 v[108:111], v[100:103], v[184:187], v[108:111]
	v_mfma_f32_16x16x32_bf16 v[88:91], v[80:83], v[208:211], v[88:91]
	v_mfma_f32_16x16x32_bf16 v[84:87], v[100:103], v[208:211], v[84:87]
	s_setprio 0
	s_setprio 1
	v_mfma_f32_16x16x32_bf16 v[152:155], v[112:115], v[156:159], v[152:155]
	v_mfma_f32_16x16x32_bf16 v[148:151], v[132:135], v[156:159], v[148:151]
	v_mfma_f32_16x16x32_bf16 v[128:131], v[112:115], v[172:175], v[128:131]
	v_mfma_f32_16x16x32_bf16 v[124:127], v[132:135], v[172:175], v[124:127]
	v_mfma_f32_16x16x32_bf16 v[104:107], v[112:115], v[180:183], v[104:107]
	v_mfma_f32_16x16x32_bf16 v[96:99], v[132:135], v[180:183], v[96:99]
	v_mfma_f32_16x16x32_bf16 v[76:79], v[112:115], v[188:191], v[76:79]
	v_mfma_f32_16x16x32_bf16 v[72:75], v[132:135], v[188:191], v[72:75]
	v_mfma_f32_16x16x32_bf16 v[152:155], v[120:123], v[168:171], v[152:155]
	v_mfma_f32_16x16x32_bf16 v[148:151], v[144:147], v[168:171], v[148:151]
	v_mfma_f32_16x16x32_bf16 v[128:131], v[120:123], v[176:179], v[128:131]
	v_mfma_f32_16x16x32_bf16 v[124:127], v[144:147], v[176:179], v[124:127]
	v_mfma_f32_16x16x32_bf16 v[104:107], v[120:123], v[184:187], v[104:107]
	v_mfma_f32_16x16x32_bf16 v[96:99], v[144:147], v[184:187], v[96:99]
	v_mfma_f32_16x16x32_bf16 v[76:79], v[120:123], v[208:211], v[76:79]
	v_mfma_f32_16x16x32_bf16 v[72:75], v[144:147], v[208:211], v[72:75]
	s_setprio 0
	s_barrier
; #define PG8_STAGE(bufoff, gbase, voff) do { _Pragma("unroll") for (int _i = 0; _i < 2; ++_i) \
;         __builtin_amdgcn_global_load_lds((const unsigned*)((const char*)(gbase) + (voff)[_i]), (PG8_LAS unsigned*)(lds + (bufoff) + ldsw + _i * 8192), 16, 0, 0); } while (0)
; #define PG8_LDA(dst, b, h) do { _Pragma("unroll") for (int m = 0; m < 4; ++m) _Pragma("unroll") for (int k = 0; k < 2; ++k) dst[m][k] = *(const PG8_LAS bf16x8*)(lds + PG8_SA(b, h) + aoff + m * 2048 + k * 1024); } while (0)
; #define PG8_MMA(ai, bj, At, Bt) do { __builtin_amdgcn_s_setprio(1); _Pragma("unroll") for (int m = 0; m < 4; ++m) _Pragma("unroll") for (int n = 0; n < 2; ++n) _Pragma("unroll") for (int k = 0; k < 2; ++k) \
;         acc[ai][bj][m][n] = __builtin_amdgcn_mfma_f32_16x16x32_bf16(Bt[n][k], At[m][k], acc[ai][bj][m][n], 0, 0, 0); __builtin_amdgcn_s_setprio(0); } while (0)
; #define PG8_WAIT_V(n) asm volatile("s_waitcnt vmcnt(" #n ")" ::: "memory")
; #define PG8_WAIT_L(n) asm volatile("s_waitcnt lgkmcnt(" #n ")" ::: "memory")
; #define PG8_BAR __builtin_amdgcn_s_barrier()
; #define PG8_SCHED __builtin_amdgcn_sched_barrier(0)
; template <class Epi, class Sched, bool ALIGN_EPI = false, bool SP2 = false>
; __device__ __forceinline__ void gemm_phase(PG8_LAS unsigned char* lds, const Gemm g, const Sched& S, const Epi& E) {
;     ...
;         for (int t = 0; t < nt; t += 2) {
;             const bool last = (t == nt - 2);
;             const char* a1 = cA + (size_t)(t + 1) * kstep;
;             const char* a2 = last ? nA : cA + (size_t)(t + 2) * kstep; const char* b2 = last ? nB : cB + (size_t)(t + 2) * kstep;
;             const char* a3 = a2 + kstep; const char* b3 = b2 + kstep;
;             if (last && has_next) S.a_ready(nxt);
;     ...
;             PG8_LDA(At, 1, 1); PG8_STAGE(PG8_SB(1, 0), b3, voffB); PG8_STAGE(PG8_SB(1, 1), b3 + hstep, voffB); PG8_STAGE(PG8_SA(1, 0), a3, voffA);
;             PG8_WAIT_V(8); PG8_WAIT_L(0); PG8_BAR; PG8_MMA(1, 0, At, B0); PG8_MMA(1, 1, At, B1); PG8_BAR; PG8_SCHED;
	s_add_i32 m0, s39, 0x17f80
	ds_read_b128 v[156:159], v236 offset:49152
	ds_read_b128 v[168:171], v236 offset:50176
	ds_read_b128 v[172:175], v236 offset:51200
	ds_read_b128 v[176:179], v236 offset:52224
	ds_read_b128 v[180:183], v236 offset:53248
	ds_read_b128 v[184:187], v236 offset:54272
	ds_read_b128 v[188:191], v236 offset:55296
	ds_read_b128 v[208:211], v236 offset:56320
	global_load_lds_dwordx4 v[198:199], off offset:128
	s_add_i32 m0, s39, 0x19f80
	s_add_u32 s26, s28, 0xb0080
	s_addc_u32 s27, s29, 0
	global_load_lds_dwordx4 v[212:213], off offset:128
	s_add_i32 m0, s39, 0x1c000
	v_lshl_add_u64 v[198:199], s[26:27], 0, v[192:193]
	global_load_lds_dwordx4 v[198:199], off
	s_add_i32 m0, s39, 0x1e000
	v_lshl_add_u64 v[198:199], s[26:27], 0, v[202:203]
	global_load_lds_dwordx4 v[198:199], off
	s_add_i32 m0, s47, 0xffffff80
	s_add_u32 s44, s44, 0x100
	s_addc_u32 s45, s45, 0
	global_load_lds_dwordx4 v[214:215], off offset:128
	s_add_i32 m0, s48, 0xffffff80
	s_mov_b64 s[26:27], s[8:9]
	global_load_lds_dwordx4 v[216:217], off offset:128
	s_waitcnt vmcnt(8) lgkmcnt(0)
	s_barrier
	s_setprio 1
	v_mfma_f32_16x16x32_bf16 v[64:67], v[68:71], v[156:159], v[64:67]
	v_mfma_f32_16x16x32_bf16 v[60:63], v[92:95], v[156:159], v[60:63]
	v_mfma_f32_16x16x32_bf16 v[48:51], v[68:71], v[172:175], v[48:51]
	v_mfma_f32_16x16x32_bf16 v[44:47], v[92:95], v[172:175], v[44:47]
	v_mfma_f32_16x16x32_bf16 v[32:35], v[68:71], v[180:183], v[32:35]
	v_mfma_f32_16x16x32_bf16 v[28:31], v[92:95], v[180:183], v[28:31]
	v_mfma_f32_16x16x32_bf16 v[16:19], v[68:71], v[188:191], v[16:19]
	v_mfma_f32_16x16x32_bf16 v[12:15], v[92:95], v[188:191], v[12:15]
	v_mfma_f32_16x16x32_bf16 v[64:67], v[80:83], v[168:171], v[64:67]
	v_mfma_f32_16x16x32_bf16 v[60:63], v[100:103], v[168:171], v[60:63]
	v_mfma_f32_16x16x32_bf16 v[48:51], v[80:83], v[176:179], v[48:51]
	v_mfma_f32_16x16x32_bf16 v[44:47], v[100:103], v[176:179], v[44:47]
	v_mfma_f32_16x16x32_bf16 v[32:35], v[80:83], v[184:187], v[32:35]
	v_mfma_f32_16x16x32_bf16 v[28:31], v[100:103], v[184:187], v[28:31]
	v_mfma_f32_16x16x32_bf16 v[16:19], v[80:83], v[208:211], v[16:19]
	v_mfma_f32_16x16x32_bf16 v[12:15], v[100:103], v[208:211], v[12:15]
	s_setprio 0
	s_setprio 1
	v_mfma_f32_16x16x32_bf16 v[56:59], v[112:115], v[156:159], v[56:59]
	v_mfma_f32_16x16x32_bf16 v[52:55], v[132:135], v[156:159], v[52:55]
	v_mfma_f32_16x16x32_bf16 v[40:43], v[112:115], v[172:175], v[40:43]
	v_mfma_f32_16x16x32_bf16 v[36:39], v[132:135], v[172:175], v[36:39]
	v_mfma_f32_16x16x32_bf16 v[24:27], v[112:115], v[180:183], v[24:27]
	v_mfma_f32_16x16x32_bf16 v[20:23], v[132:135], v[180:183], v[20:23]
	v_mfma_f32_16x16x32_bf16 v[8:11], v[112:115], v[188:191], v[8:11]
	v_mfma_f32_16x16x32_bf16 v[4:7], v[132:135], v[188:191], v[4:7]
	v_mfma_f32_16x16x32_bf16 v[56:59], v[120:123], v[168:171], v[56:59]
	v_mfma_f32_16x16x32_bf16 v[52:55], v[144:147], v[168:171], v[52:55]
	v_mfma_f32_16x16x32_bf16 v[40:43], v[120:123], v[176:179], v[40:43]
	v_mfma_f32_16x16x32_bf16 v[36:39], v[144:147], v[176:179], v[36:39]
	v_mfma_f32_16x16x32_bf16 v[24:27], v[120:123], v[184:187], v[24:27]
	v_mfma_f32_16x16x32_bf16 v[20:23], v[144:147], v[184:187], v[20:23]
	v_mfma_f32_16x16x32_bf16 v[8:11], v[120:123], v[208:211], v[8:11]
	v_mfma_f32_16x16x32_bf16 v[4:7], v[144:147], v[208:211], v[4:7]
	s_setprio 0
	s_barrier
	s_add_i32 s53, s53, 2
	s_cmp_gt_u32 s53, 41
	s_cbranch_scc0 .LBB0_480
	s_and_b64 vcc, exec, s[20:21]
	s_cbranch_vccz .LBB0_483
	s_barrier
